# P3 expert loop hand-rescheduled (saddr loads, fixed accumulators, no copies; bit-identical) + N2 row-max via v_max3 without self-max copies
# speedup vs baseline: 1.0196x; 1.0196x over previous
; __device__ __forceinline__ float exp2f_(float x) { return __builtin_amdgcn_exp2f(x); }
; __device__ __forceinline__ f32x4 mfma16(bf16x8 a, bf16x8 b, f32x4 c) { return __builtin_amdgcn_mfma_f32_16x16x32_bf16(a, b, c, 0, 0, 0); }
; __device__ __forceinline__ void nsa_block_step(const bf16_t* Ks, const bf16_t* VT, const bf16x8 (&qf)[2][2], f32x4 (&O)[2][4], float (&m)[2], float (&l)[2],
;                                                int klo, int khi, int r, int q) {
;     ...
;     bf16x8 pbv[2][2];
; #pragma unroll
;     for (int x = 0; x < 2; x++) {
;         float mx = fmaxf(fmaxf(fmaxf(s[x][0][0], s[x][0][1]), fmaxf(s[x][0][2], s[x][0][3])), fmaxf(fmaxf(s[x][1][0], s[x][1][1]), fmaxf(s[x][1][2], s[x][1][3])));
;         mx = fmaxf(mx, fmaxf(fmaxf(fmaxf(s[x][2][0], s[x][2][1]), fmaxf(s[x][2][2], s[x][2][3])), fmaxf(fmaxf(s[x][3][0], s[x][3][1]), fmaxf(s[x][3][2], s[x][3][3]))));
;         mx = xrow_max(mx);
;         const float mnew = fmaxf(m[x], mx);
;         const float alpha = exp2f_(m[x] - mnew);
;         m[x] = mnew;
;         float ls = 0.f;
; #pragma unroll
;         for (int kt = 0; kt < 4; kt++)
; #pragma unroll
;             for (int j = 0; j < 4; j++) { const float pv = exp2f_(s[x][kt][j] - mnew); s[x][kt][j] = pv; ls += pv; }
;         l[x] = l[x] * alpha + ls;
; #pragma unroll
;         for (int dt = 0; dt < 4; dt++) O[x][dt] *= alpha;
; #pragma unroll
;         for (int s2 = 0; s2 < 2; s2++) {
;             const u32x4 t4 = {pack2(s[x][2 * s2][0], s[x][2 * s2][1]), pack2(s[x][2 * s2][2], s[x][2 * s2][3]),
;                               pack2(s[x][2 * s2 + 1][0], s[x][2 * s2 + 1][1]), pack2(s[x][2 * s2 + 1][2], s[x][2 * s2 + 1][3])};
;             pbv[x][s2] = __builtin_bit_cast(bf16x8, t4);
;         }
;     }
; #pragma unroll
;     for (int s2 = 0; s2 < 2; s2++)
; #pragma unroll
;         for (int dt = 0; dt < 4; dt++) {
;             const u32x2 lo = *(const u32x2*)(VT + (dt * 16 + r) * 72 + (2 * s2) * 16 + 4 * q);
;             const u32x2 hi = *(const u32x2*)(VT + (dt * 16 + r) * 72 + (2 * s2 + 1) * 16 + 4 * q);
;             const bf16x8 va = mk_frag(lo, hi);
; #pragma unroll
;             for (int x = 0; x < 2; x++) O[x][dt] = mfma16(va, pbv[x][s2], O[x][dt]);
;         }
.LBB0_628:
	v_max3_f32 v88, v80, v81, v82
	v_max3_f32 v164, v68, v69, v70
	v_max3_f32 v97, v72, v73, v74
	v_max3_f32 v165, v64, v65, v66
	v_max3_f32 v104, v84, v85, v86
	v_max3_f32 v166, v60, v61, v62
	v_max3_f32 v105, v76, v77, v78
	v_max3_f32 v167, v56, v57, v58
	v_max3_f32 v88, v88, v83, v75
	v_max3_f32 v164, v164, v71, v67
	v_max3_f32 v97, v97, v87, v79
	v_max3_f32 v165, v165, v63, v59
	v_max3_f32 v88, v88, v97, v104
	v_max3_f32 v164, v164, v165, v166
	v_max_f32_e32 v88, v88, v105
	v_max_f32_e32 v164, v164, v167
	v_mov_b32_e32 v97, v88
	v_mov_b32_e32 v165, v164
	s_nop 0
	v_permlane16_swap_b32_e32 v88, v97
	s_nop 0
	v_permlane16_swap_b32_e32 v164, v165
	v_max_f32_e32 v88, v88, v97
	v_max_f32_e32 v164, v164, v165
	v_mov_b32_e32 v97, v88
	v_mov_b32_e32 v165, v164
	s_nop 0
	v_permlane32_swap_b32_e32 v88, v97
	s_nop 0
	v_permlane32_swap_b32_e32 v164, v165
	v_max3_f32 v88, v103, v88, v97
	v_sub_f32_e32 v72, v72, v88
	v_exp_f32_e32 v105, v72
	v_sub_f32_e32 v72, v73, v88
	v_exp_f32_e32 v109, v72
	v_sub_f32_e32 v72, v74, v88
	v_exp_f32_e32 v107, v72
	v_sub_f32_e32 v72, v75, v88
	v_sub_f32_e32 v80, v80, v88
	v_exp_f32_e32 v111, v72
	v_sub_f32_e32 v72, v84, v88
	v_exp_f32_e32 v117, v80
	v_sub_f32_e32 v80, v81, v88
	v_exp_f32_e32 v73, v72
	v_sub_f32_e32 v72, v85, v88
	v_exp_f32_e32 v113, v80
	v_sub_f32_e32 v80, v82, v88
	v_exp_f32_e32 v75, v72
	v_sub_f32_e32 v72, v86, v88
	v_exp_f32_e32 v115, v80
	v_sub_f32_e32 v80, v83, v88
	v_exp_f32_e32 v83, v72
	v_sub_f32_e32 v72, v87, v88
	v_exp_f32_e32 v81, v72
	v_sub_f32_e32 v72, v76, v88
	v_exp_f32_e32 v85, v72
	v_sub_f32_e32 v72, v77, v88
	v_exp_f32_e32 v87, v72
	v_sub_f32_e32 v72, v78, v88
	v_exp_f32_e32 v77, v72
	v_sub_f32_e32 v72, v79, v88
	v_exp_f32_e32 v79, v72
	v_sub_f32_e32 v97, v103, v88
	v_exp_f32_e32 v103, v80
	v_exp_f32_e32 v76, v97
	v_max3_f32 v97, v102, v164, v165
	v_sub_f32_e32 v64, v64, v97
	v_sub_f32_e32 v68, v68, v97
	v_exp_f32_e32 v104, v64
	v_sub_f32_e32 v64, v65, v97
	v_sub_f32_e32 v78, v102, v97
	v_exp_f32_e32 v116, v68
	v_sub_f32_e32 v68, v69, v97
	v_exp_f32_e32 v108, v64
	v_sub_f32_e32 v64, v66, v97
	v_exp_f32_e32 v112, v68
	v_exp_f32_e32 v106, v64
	v_sub_f32_e32 v64, v67, v97
	v_sub_f32_e32 v60, v60, v97
	v_exp_f32_e32 v160, v78
	v_add_u32_e32 v78, 0x4800, v135
	v_exp_f32_e32 v110, v64
	v_exp_f32_e32 v72, v60
	v_sub_f32_e32 v60, v61, v97
	ds_read2_b64 v[64:67], v78 offset1:4
	v_exp_f32_e32 v74, v60
	v_sub_f32_e32 v60, v62, v97
	v_sub_f32_e32 v68, v70, v97
	v_exp_f32_e32 v82, v60
	v_sub_f32_e32 v60, v63, v97
	v_exp_f32_e32 v114, v68
	v_sub_f32_e32 v68, v71, v97
	v_pk_add_f32 v[156:157], v[116:117], 0 op_sel_hi:[1,0]
	v_exp_f32_e32 v80, v60
	v_cvt_pk_bf16_f32 v60, v116, v112
	v_add_u32_e32 v116, 0x5000, v135
	v_exp_f32_e32 v102, v68
	ds_read2_b64 v[68:71], v116 offset0:32 offset1:36
	v_mov_b32_e32 v161, v76
	v_pk_mul_f32 v[146:147], v[54:55], v[76:77] op_sel_hi:[1,0]
	v_pk_mul_f32 v[144:145], v[52:53], v[76:77] op_sel_hi:[1,0]
	v_cvt_pk_bf16_f32 v52, v117, v113
	v_cvt_pk_bf16_f32 v53, v115, v103
	v_cvt_pk_bf16_f32 v54, v105, v109
	v_cvt_pk_bf16_f32 v55, v107, v111
	v_pk_mul_f32 v[38:39], v[38:39], v[160:161] op_sel_hi:[1,0]
	v_pk_mul_f32 v[36:37], v[36:37], v[160:161] op_sel_hi:[1,0]
	v_cvt_pk_bf16_f32 v61, v114, v102
	v_cvt_pk_bf16_f32 v62, v104, v108
	v_cvt_pk_bf16_f32 v63, v106, v110
	v_add_u32_e32 v117, 0x5800, v135
	s_waitcnt lgkmcnt(1)
	v_mfma_f32_16x16x32_bf16 v[144:147], v[64:67], v[52:55], v[144:147]
	v_mul_f32_e64 v150, v50, v76
	v_mul_f32_e64 v151, v51, v76
	v_pk_mul_f32 v[148:149], v[48:49], v[76:77] op_sel_hi:[1,0]
	v_pk_mul_f32 v[34:35], v[34:35], v[160:161] op_sel_hi:[1,0]
	v_mfma_f32_16x16x32_bf16 v[36:39], v[64:67], v[60:63], v[36:39]
	ds_read2_b64 v[64:67], v117 offset0:64 offset1:68
	v_pk_mul_f32 v[32:33], v[32:33], v[160:161] op_sel_hi:[1,0]
	v_add_u32_e32 v162, 0x6000, v135
	s_waitcnt lgkmcnt(1)
	v_mfma_f32_16x16x32_bf16 v[148:151], v[68:71], v[52:55], v[148:151]
	v_mul_f32_e64 v50, v46, v76
	v_mul_f32_e64 v51, v47, v76
	v_pk_mul_f32 v[48:49], v[44:45], v[76:77] op_sel_hi:[1,0]
	v_pk_mul_f32 v[46:47], v[42:43], v[76:77] op_sel_hi:[1,0]
	v_mfma_f32_16x16x32_bf16 v[32:35], v[68:71], v[60:63], v[32:35]
	ds_read2_b64 v[68:71], v162 offset0:96 offset1:100
	v_pk_mul_f32 v[44:45], v[40:41], v[76:77] op_sel_hi:[1,0]
	v_sub_f32_e32 v56, v56, v97
	s_waitcnt lgkmcnt(1)
	v_mfma_f32_16x16x32_bf16 v[152:155], v[64:67], v[52:55], v[48:51]
	v_mul_f32_e64 v30, v30, v160
	v_mul_f32_e64 v31, v31, v160
	v_pk_mul_f32 v[28:29], v[28:29], v[160:161] op_sel_hi:[1,0]
	v_exp_f32_e32 v84, v56
	v_sub_f32_e32 v48, v58, v97
	v_exp_f32_e32 v76, v48
	ds_read2_b64 v[48:51], v78 offset0:8 offset1:12
	v_sub_f32_e32 v56, v57, v97
	v_mfma_f32_16x16x32_bf16 v[28:31], v[64:67], v[60:63], v[28:31]
	v_exp_f32_e32 v86, v56
	v_cvt_pk_bf16_f32 v40, v73, v75
	v_cvt_pk_bf16_f32 v41, v83, v81
	s_waitcnt lgkmcnt(1)
	v_mfma_f32_16x16x32_bf16 v[64:67], v[68:71], v[52:55], v[44:47]
	v_cvt_pk_bf16_f32 v42, v85, v87
	v_cvt_pk_bf16_f32 v43, v77, v79
	v_cvt_pk_bf16_f32 v56, v72, v74
	v_sub_f32_e32 v44, v59, v97
	v_exp_f32_e32 v78, v44
	ds_read2_b64 v[44:47], v116 offset0:40 offset1:44
	v_cvt_pk_bf16_f32 v57, v82, v80
	v_cvt_pk_bf16_f32 v58, v84, v86
	v_cvt_pk_bf16_f32 v59, v76, v78
	v_pk_mul_f32 v[26:27], v[26:27], v[160:161] op_sel_hi:[1,0]
	v_pk_mul_f32 v[24:25], v[24:25], v[160:161] op_sel_hi:[1,0]
	s_waitcnt lgkmcnt(1)
	v_mfma_f32_16x16x32_bf16 v[52:55], v[48:51], v[40:43], v[144:147]
	v_cmp_ne_u32_e32 vcc, v141, v143
	v_mfma_f32_16x16x32_bf16 v[36:39], v[48:51], v[56:59], v[36:39]
	v_add_f32_e64 v48, v112, v156
	v_add_f32_e64 v49, v113, v157
	v_mfma_f32_16x16x32_bf16 v[24:27], v[68:71], v[60:63], v[24:27]
	v_add_f32_e64 v68, v114, v48
	v_add_f32_e64 v69, v115, v49
	ds_read2_b64 v[60:63], v117 offset0:72 offset1:76
	v_pk_add_f32 v[68:69], v[102:103], v[68:69]
	s_waitcnt lgkmcnt(1)
; __device__ __forceinline__ float sigmoidf_(float x) { return __builtin_amdgcn_rcpf(1.f + __expf(-x)); }
; __device__ __forceinline__ f32x4 mfma16(bf16x8 a, bf16x8 b, f32x4 c) { return __builtin_amdgcn_mfma_f32_16x16x32_bf16(a, b, c, 0, 0, 0); }
; __device__ __forceinline__ void nsa_block_step(const bf16_t* Ks, const bf16_t* VT, const bf16x8 (&qf)[2][2], f32x4 (&O)[2][4], float (&m)[2], float (&l)[2],
;                                                int klo, int khi, int r, int q) {
;     ...
; #pragma unroll
;     for (int s2 = 0; s2 < 2; s2++)
; #pragma unroll
;         for (int dt = 0; dt < 4; dt++) {
;             const u32x2 lo = *(const u32x2*)(VT + (dt * 16 + r) * 72 + (2 * s2) * 16 + 4 * q);
;             const u32x2 hi = *(const u32x2*)(VT + (dt * 16 + r) * 72 + (2 * s2 + 1) * 16 + 4 * q);
;             const bf16x8 va = mk_frag(lo, hi);
; #pragma unroll
;             for (int x = 0; x < 2; x++) O[x][dt] = mfma16(va, pbv[x][s2], O[x][dt]);
;         }
; }
; __device__ void phaseN2_task(const Params& p, int task, char* lds, bf16_t* ydst, int ystride, volatile unsigned* uex, char* ldsb) {
;     ...
;             if (nbr != br) {
; #pragma unroll
;                 for (int x = 0; x < 2; x++) {
;                     float lt = l[x];
;                     lt = xrow_sum(lt);
;                     const float sc = sigmoidf_(br == 0 ? gatev[1][x] : gatev[2][x]) / lt;
; #pragma unroll
;                     for (int dt = 0; dt < 4; dt++) { ofl[(wave * 8 + x * 4 + dt) * 64 + lane] += sc * O[x][dt]; O[x][dt] = (f32x4){0.f, 0.f, 0.f, 0.f}; }
;                     m[x] = -1e30f; l[x] = 0.f;
;                 }
;             }
	v_mfma_f32_16x16x32_bf16 v[48:51], v[44:47], v[40:43], v[148:151]
	v_add_f32_e64 v68, v104, v68
	v_add_f32_e64 v69, v105, v69
	v_pk_add_f32 v[68:69], v[108:109], v[68:69]
	v_mfma_f32_16x16x32_bf16 v[32:35], v[44:47], v[56:59], v[32:35]
	v_add_f32_e64 v44, v106, v68
	v_add_f32_e64 v45, v107, v69
	ds_read2_b64 v[68:71], v162 offset0:104 offset1:108
	v_pk_add_f32 v[102:103], v[110:111], v[44:45]
	s_waitcnt lgkmcnt(1)
	v_mfma_f32_16x16x32_bf16 v[44:47], v[60:63], v[40:43], v[152:155]
	v_add_f32_e64 v72, v72, v102
	v_add_f32_e64 v73, v73, v103
	v_pk_add_f32 v[72:73], v[74:75], v[72:73]
	v_mfma_f32_16x16x32_bf16 v[28:31], v[60:63], v[56:59], v[28:31]
	v_add_f32_e64 v72, v82, v72
	v_add_f32_e64 v73, v83, v73
	v_pk_add_f32 v[60:61], v[80:81], v[72:73]
	s_waitcnt lgkmcnt(0)
	v_mfma_f32_16x16x32_bf16 v[40:43], v[68:71], v[40:43], v[64:67]
	v_add_f32_e64 v60, v84, v60
	v_add_f32_e64 v61, v85, v61
	v_pk_add_f32 v[60:61], v[86:87], v[60:61]
	v_mfma_f32_16x16x32_bf16 v[24:27], v[68:71], v[56:59], v[24:27]
	v_add_f32_e64 v60, v76, v60
	v_add_f32_e64 v61, v77, v61
	v_pk_add_f32 v[60:61], v[78:79], v[60:61]
	s_nop 0
	v_pk_fma_f32 v[100:101], v[100:101], v[160:161], v[60:61]
	s_and_saveexec_b64 s[6:7], vcc
	s_cbranch_execz .LBB0_617
	s_mov_b64 vcc, s[4:5]
	v_cndmask_b32_sdwa v57, v128, v127, vcc dst_sel:WORD_1 dst_unused:UNUSED_PAD src0_sel:DWORD src1_sel:DWORD
	v_mov_b32_e32 v56, v101
	v_mul_f32_e32 v57, 0xbfb8aa3b, v57
	v_exp_f32_e32 v57, v57
	v_permlane16_swap_b32_e32 v101, v56
	v_add_f32_e32 v56, v101, v56
	v_add_f32_e32 v57, 1.0, v57
	v_rcp_f32_e32 v60, v57
	v_mov_b32_e32 v58, v56
	s_nop 1
	v_permlane32_swap_b32_e32 v56, v58
	v_add_f32_e32 v61, v56, v58
	v_div_scale_f32 v56, s[10:11], v61, v61, v60
	v_rcp_f32_e32 v62, v56
	v_mov_b32_e32 v97, 0xf149f2ca
	v_mov_b32_e32 v88, 0xf149f2ca
	v_fma_f32 v57, -v56, v62, 1.0
	v_fmac_f32_e32 v62, v57, v62
	v_div_scale_f32 v57, vcc, v60, v61, v60
	v_mul_f32_e32 v63, v57, v62
	v_fma_f32 v58, -v56, v63, v57
	v_fmac_f32_e32 v63, v58, v62
	v_fma_f32 v64, -v56, v63, v57
	ds_read_b128 v[56:59], v131 offset:35840
	v_div_fmas_f32 v62, v64, v62, v63
	v_div_fixup_f32 v64, v62, v61, v60
	ds_read_b128 v[60:63], v131 offset:36864
	s_waitcnt lgkmcnt(1)
	v_pk_fma_f32 v[54:55], v[54:55], v[64:65], v[58:59] op_sel_hi:[1,0,1]
	v_pk_fma_f32 v[52:53], v[52:53], v[64:65], v[56:57] op_sel_hi:[1,0,1]
	ds_write_b128 v131, v[52:55] offset:35840
	ds_read_b128 v[52:55], v131 offset:37888
	s_waitcnt lgkmcnt(2)
	v_pk_fma_f32 v[50:51], v[50:51], v[64:65], v[62:63] op_sel_hi:[1,0,1]
	v_pk_fma_f32 v[48:49], v[48:49], v[64:65], v[60:61] op_sel_hi:[1,0,1]
	ds_write_b128 v131, v[48:51] offset:36864
	ds_read_b128 v[48:51], v131 offset:38912
	s_waitcnt lgkmcnt(2)
	v_pk_fma_f32 v[46:47], v[46:47], v[64:65], v[54:55] op_sel_hi:[1,0,1]
	v_pk_fma_f32 v[44:45], v[44:45], v[64:65], v[52:53] op_sel_hi:[1,0,1]
	ds_write_b128 v131, v[44:47] offset:37888
	v_cndmask_b32_e64 v45, v133, v93, s[4:5]
	v_lshlrev_b32_e32 v45, 16, v45
	v_mul_f32_e32 v45, 0xbfb8aa3b, v45
	v_exp_f32_e32 v45, v45
	v_mov_b32_e32 v44, v100
	s_nop 1
	v_permlane16_swap_b32_e32 v100, v44
	v_add_f32_e32 v45, 1.0, v45
	v_add_f32_e32 v44, v100, v44
	v_rcp_f32_e32 v45, v45
	v_mov_b32_e32 v46, v44
	s_nop 1
	v_permlane32_swap_b32_e32 v44, v46
	v_add_f32_e32 v44, v44, v46
	v_div_scale_f32 v46, s[4:5], v44, v44, v45
	v_rcp_f32_e32 v47, v46
	s_waitcnt lgkmcnt(1)
	v_pk_fma_f32 v[42:43], v[42:43], v[64:65], v[50:51] op_sel_hi:[1,0,1]
	v_pk_fma_f32 v[40:41], v[40:41], v[64:65], v[48:49] op_sel_hi:[1,0,1]
	ds_write_b128 v131, v[40:43] offset:38912
	v_fma_f32 v40, -v46, v47, 1.0
	v_fmac_f32_e32 v47, v40, v47
	v_div_scale_f32 v40, vcc, v45, v44, v45
	v_mul_f32_e32 v48, v40, v47
	v_fma_f32 v41, -v46, v48, v40
	v_fmac_f32_e32 v48, v41, v47
	v_fma_f32 v46, -v46, v48, v40
	ds_read_b128 v[40:43], v131 offset:39936
	v_div_fmas_f32 v46, v46, v47, v48
	v_div_fixup_f32 v48, v46, v44, v45
	ds_read_b128 v[44:47], v131 offset:40960
	s_waitcnt lgkmcnt(1)
	v_pk_fma_f32 v[38:39], v[38:39], v[48:49], v[42:43] op_sel_hi:[1,0,1]
	v_pk_fma_f32 v[36:37], v[36:37], v[48:49], v[40:41] op_sel_hi:[1,0,1]
	ds_write_b128 v131, v[36:39] offset:39936
	ds_read_b128 v[36:39], v131 offset:41984
	ds_read_b128 v[40:43], v131 offset:43008
	s_waitcnt lgkmcnt(3)
	v_pk_fma_f32 v[34:35], v[34:35], v[48:49], v[46:47] op_sel_hi:[1,0,1]
	v_pk_fma_f32 v[32:33], v[32:33], v[48:49], v[44:45] op_sel_hi:[1,0,1]
	ds_write_b128 v131, v[32:35] offset:40960
	s_waitcnt lgkmcnt(2)
	v_pk_fma_f32 v[30:31], v[30:31], v[48:49], v[38:39] op_sel_hi:[1,0,1]
	s_waitcnt lgkmcnt(1)
	v_pk_fma_f32 v[26:27], v[26:27], v[48:49], v[42:43] op_sel_hi:[1,0,1]
	v_pk_fma_f32 v[24:25], v[24:25], v[48:49], v[40:41] op_sel_hi:[1,0,1]
	v_pk_fma_f32 v[28:29], v[28:29], v[48:49], v[36:37] op_sel_hi:[1,0,1]
	ds_write_b128 v131, v[24:27] offset:43008
	v_mov_b32_e32 v24, 0
	ds_write_b128 v131, v[28:31] offset:41984
	v_mov_b32_e32 v25, v24
	v_mov_b32_e32 v26, v24
	v_mov_b32_e32 v27, v24
	v_mov_b32_e32 v28, v24
	v_mov_b32_e32 v29, v24
	v_mov_b32_e32 v30, v24
	v_mov_b32_e32 v31, v24
	v_mov_b32_e32 v32, v24
	v_mov_b32_e32 v33, v24
	v_mov_b32_e32 v34, v24
	v_mov_b32_e32 v35, v24
	v_mov_b32_e32 v36, v24
	v_mov_b32_e32 v37, v24
	v_mov_b32_e32 v38, v24
	v_mov_b32_e32 v39, v24
	v_mov_b32_e32 v40, v24
	v_mov_b32_e32 v41, v24
	v_mov_b32_e32 v42, v24
	v_mov_b32_e32 v43, v24
	v_mov_b32_e32 v44, v24
	v_mov_b32_e32 v45, v24
	v_mov_b32_e32 v46, v24
	v_mov_b32_e32 v47, v24
	v_mov_b32_e32 v48, v24
	v_mov_b32_e32 v49, v24
	v_mov_b32_e32 v50, v24
	v_mov_b32_e32 v51, v24
	v_mov_b32_e32 v52, v24
	v_mov_b32_e32 v53, v24
	v_mov_b32_e32 v54, v24
	v_mov_b32_e32 v55, v24
	v_mov_b32_e32 v100, v24
	v_mov_b32_e32 v101, v24
	s_branch .LBB0_617

; __device__ __forceinline__ int vblk() { return (int)blockIdx.x * 2 + half_id(); }
; __device__ __forceinline__ int vgrid() { return (int)gridDim.x * 2; }
; __device__ __forceinline__ void p3_load_u(u32x2 (&ur)[4], P3Sc& sc, const unsigned char* __restrict__ UQ, const float* __restrict__ tsc,
;                                           int lane, int ul, int g, const unsigned* rec) {
; #pragma unroll
;     for (int u = 0; u < 4; u++) ur[u] = *(const u32x2*)(UQ + (size_t)rec[4 * g + u] * 512 + lane * 8);
;     sc.gm = __uint_as_float(rec[128 + 4 * g + ul]);
;     sc.su = __uint_as_float(rec[512 + 4 * g + ul]);
;     sc.sv = 1.f;
; }
; __device__ __forceinline__ void p3_load_v(u32x2 (&vr)[4], const unsigned char* __restrict__ VQ, int lane, int g, const unsigned* rec) {
; #pragma unroll
;     for (int u = 0; u < 4; u++) vr[u] = *(const u32x2*)(VQ + (size_t)rec[4 * g + u] * 512 + lane * 8);
; __device__ void phaseP3(const Params& p, float* dstp, char* lds) {
;     const int tid_ = TIDX; const int lane = tid_ & 63, wave = tid_ >> 6;
;     const unsigned char* UQ = (const unsigned char*)(p.ws + OFF_UB);
;     const unsigned char* VQ = UQ + 16777216;
;     const float* tsc = (const float*)(p.ws + OFF_UB + 33554432);
;     const int ul = ((lane & 1) << 1) | ((lane >> 1) & 1);
;     constexpr int TPW = 2;
;     unsigned* recs = (unsigned*)(lds + wave * TPW * P3_REC);
;     for (int tb = (vblk() * 4 + wave) * TPW; tb < NTOK; tb += vgrid() * 4 * TPW) {
.LBB0_1040:
	s_or_b64 exec, exec, s[4:5]
	v_readfirstlane_b32 s0, v158
	v_readlane_b32 s1, v222, 0
	s_lshr_b32 s0, s0, 5
	v_mov_b32_e32 v1, v158
	s_lshl_b32 s1, s1, 4
	s_and_b32 s0, s0, 0x7fffff8
	s_waitcnt lgkmcnt(0)
	s_barrier
	s_add_i32 s0, s0, s1
	v_bfe_u32 v0, v1, 6, 2
	v_lshl_or_b32 v8, v0, 1, s0
	s_movk_i32 s0, 0x4000
	v_cmp_gt_i32_e32 vcc, s0, v8
	s_and_saveexec_b64 s[0:1], vcc
	s_cbranch_execz .LBB0_1077
	s_movk_i32 s8, 0x1400
	v_mov_b32_e32 v2, s33
	v_mad_u32_u24 v11, v0, s8, v2
	v_and_b32_e32 v2, 64, v159
	v_add_u32_e32 v2, 64, v2
	v_xor_b32_e32 v3, 32, v159
	v_cmp_lt_i32_e32 vcc, v3, v2
	s_load_dwordx4 s[20:23], s[80:81], 0xd0
	s_load_dwordx2 s[4:5], s[80:81], 0x38
	v_cndmask_b32_e32 v3, v159, v3, vcc
	v_lshlrev_b32_e32 v112, 2, v3
	v_xor_b32_e32 v3, 16, v159
	v_cmp_lt_i32_e32 vcc, v3, v2
	v_and_b32_e32 v10, 63, v1
	v_mov_b32_e32 v13, 0
	v_cndmask_b32_e32 v3, v159, v3, vcc
	v_lshlrev_b32_e32 v113, 2, v3
	v_xor_b32_e32 v3, 8, v159
	v_cmp_lt_i32_e32 vcc, v3, v2
	v_lshlrev_b32_e32 v12, 4, v10
	s_mov_b64 s[0:1], 0x9c00000
	v_cndmask_b32_e32 v3, v159, v3, vcc
	v_lshlrev_b32_e32 v114, 2, v3
	v_xor_b32_e32 v3, 4, v159
	v_cmp_lt_i32_e32 vcc, v3, v2
	s_lshl_b32 s36, s72, 4
	v_bfrev_b32_e32 v4, v1
	v_cndmask_b32_e32 v3, v159, v3, vcc
	v_lshlrev_b32_e32 v115, 2, v3
	v_xor_b32_e32 v3, 2, v159
	v_cmp_lt_i32_e32 vcc, v3, v2
	s_waitcnt vmcnt(3) lgkmcnt(0)
	v_lshl_add_u64 v[18:19], s[20:21], 0, v[12:13]
	s_add_u32 s20, s22, 0xdd00000
	v_cndmask_b32_e32 v3, v159, v3, vcc
	v_lshlrev_b32_e32 v116, 2, v3
	v_xor_b32_e32 v3, 1, v159
	v_cmp_lt_i32_e32 vcc, v3, v2
	s_addc_u32 s21, s23, 0
	v_mov_b32_e32 v5, v13
	v_cndmask_b32_e32 v2, v159, v3, vcc
	v_lshlrev_b32_e32 v117, 2, v2
	v_lshlrev_b32_e32 v2, 3, v10
	v_mov_b32_e32 v3, v13
	v_lshl_add_u64 v[2:3], s[22:23], 0, v[2:3]
	v_lshl_add_u64 v[14:15], v[2:3], 0, s[0:1]
	s_mov_b64 s[0:1], 0xac00000
	v_lshl_add_u64 v[16:17], v[2:3], 0, s[0:1]
	v_and_b32_e32 v2, 1, v1
	v_lshrrev_b32_e32 v3, 28, v4
	v_cmp_eq_u32_e64 s[0:1], 0, v2
	v_lshlrev_b32_e32 v2, 6, v10
	v_and_b32_e32 v6, 12, v3
	v_lshlrev_b32_e32 v4, 5, v10
	s_add_u32 s24, s22, 0xe500000
	v_mov_b32_e32 v3, v13
	v_and_b32_e32 v1, 2, v1
	v_add_u32_e32 v118, v11, v2
	v_lshl_add_u64 v[4:5], s[22:23], 0, v[4:5]
	s_mov_b64 s[6:7], 0x1c00000
	s_addc_u32 s25, s23, 0
	s_waitcnt vmcnt(1)
	v_lshl_add_u64 v[24:25], s[4:5], 0, v[2:3]
	v_mov_b32_e32 v2, s33
	v_cmp_eq_u32_e64 s[2:3], 0, v1
	v_mul_i32_i24_e32 v1, 0xffffffd0, v10
	v_lshl_add_u64 v[20:21], v[4:5], 0, s[6:7]
	s_add_u32 s26, s22, 0xbc00000
	s_mov_b64 s[6:7], 0xbd00000
	v_mad_u32_u24 v0, v0, s8, v2
	s_movk_i32 s4, 0x210
	v_add_u32_e32 v119, v11, v6
	s_addc_u32 s27, s23, 0
	v_lshl_add_u64 v[22:23], v[4:5], 0, s[6:7]
	v_add3_u32 v120, v0, v6, s4
	v_add_u32_e32 v121, 16, v0
	s_mov_b64 s[28:29], 0
	s_mov_b32 s33, 0x42ee0000
	v_mov_b32_e32 v122, 0x80
	s_movk_i32 s37, 0x800
	v_mov_b32_e32 v123, 0x800
	v_mov_b32_e32 v124, 0x8000
	v_mov_b32_e32 v125, 0x80000
	s_mov_b32 s38, 0x800000
	v_mov_b32_e32 v126, 0x800000
	v_bfrev_b32_e32 v127, 16
	v_add_u32_e32 v128, v118, v1
	s_mov_b32 s39, 0x3e6d3388
	v_mov_b32_e32 v129, 0xbf3a00e3
	v_lshlrev_b32_e32 v26, 2, v12
	s_mov_b64 s[30:31], 0x9000
	s_mov_b32 s40, 0x9000
	v_mov_b32_e32 v130, 0x358637bd
	s_movk_i32 s41, 0x3fff
	s_add_u32 s50, s22, 0x9c00000
	s_addc_u32 s51, s23, 0
	s_add_u32 s52, s22, 0xac00000
	s_addc_u32 s53, s23, 0
	v_lshlrev_b32_e32 v136, 3, v159

; __device__ __forceinline__ void p3_dots(const u32x2 (&ur)[4], const unsigned* rec, int lane, int (&pt)[4]) {
;     const u32x4 qh = *(const u32x4*)(rec + 256 + lane * 4);
; #pragma unroll
;     for (int u = 0; u < 4; u++) {
;         const int w0 = (int)ur[u].x, w1 = (int)ur[u].y;
;         int dh = __builtin_amdgcn_sdot8(w0, (int)qh.x, 0, false);
;         dh = __builtin_amdgcn_sdot8(w1, (int)qh.z, dh, false);
;         int dl = __builtin_amdgcn_sdot8(w0, (int)qh.y, 0, false);
;         dl = __builtin_amdgcn_sdot8(w1, (int)qh.w, dl, false);
;         pt[u] = (dh << 4) + dl;
;     }
; }
; template <int CTRL> __device__ __forceinline__ int dpp_i(int v) { return __builtin_amdgcn_mov_dpp(v, CTRL, 0xF, 0xF, true); }
; __device__ __forceinline__ int xrow_sum_i(int v) {
;     const auto a = __builtin_amdgcn_permlane16_swap((unsigned)v, (unsigned)v, false, false);
;     v = (int)a[0] + (int)a[1];
;     const auto b = __builtin_amdgcn_permlane32_swap((unsigned)v, (unsigned)v, false, false);
;     return (int)b[0] + (int)b[1];
; }
; __device__ __forceinline__ float p3_weight(const int (&pt)[4], int lane, float sh, int hs8, const P3Sc& sc) {
;     int m2[2], m1;
;     const bool c0 = lane & 1;
; #pragma unroll
;     for (int j = 0; j < 2; j++) { const int keep = c0 ? pt[j + 2] : pt[j], send = c0 ? pt[j] : pt[j + 2]; m2[j] = keep + dpp_i<0xB1>(send); }
;     const bool c1 = lane & 2;
;     { const int keep = c1 ? m2[1] : m2[0], send = c1 ? m2[0] : m2[1]; m1 = keep + dpp_i<0x4E>(send); }
;     m1 += dpp_i<0x124>(m1);
;     m1 += dpp_i<0x128>(m1);
;     m1 = xrow_sum_i(m1);
;     const float aval = (float)(m1 - hs8) * sc.su;
;     return sc.gm * gelu_erf(aval);
; }
; __device__ __forceinline__ void p3_axpy(const u32x2 (&vr)[4], float ws, f32x2 (&acc)[8]) {
; #pragma unroll
;     for (int u = 0; u < 4; u++) {
;         const int la = ((u >> 1) & 1) | ((u & 1) << 1);
;         const float wu = __builtin_bit_cast(float, __builtin_amdgcn_readlane(__builtin_bit_cast(int, ws), la));
;         const f32x2 w2 = {wu, wu};
;         const unsigned vw[2] = {vr[u].x, vr[u].y};
; #pragma unroll
;         for (int i = 0; i < 2; i++) {
;             acc[i * 4 + 0] = __builtin_elementwise_fma(w2, __builtin_amdgcn_cvt_scalef32_pk_f32_fp4(vw[i], 1.0f, 0), acc[i * 4 + 0]);
.LBB0_1075:
	v_add_u32_e32 v134, s5, v121
	v_add_u32_e32 v135, s5, v120
	ds_read_b128 v[140:143], v134
	s_waitcnt vmcnt(12) lgkmcnt(1)
	v_dot8_i32_i4 v12, v80, v4, 0
	v_dot8_i32_i4 v27, v80, v5, 0
	v_dot8_i32_i4 v131, v74, v4, 0
	v_dot8_i32_i4 v132, v74, v5, 0
	v_dot8_i32_i4 v12, v81, v6, v12
	v_dot8_i32_i4 v27, v81, v7, v27
	v_dot8_i32_i4 v131, v75, v6, v131
	v_dot8_i32_i4 v132, v75, v7, v132
	v_dot8_i32_i4 v133, v84, v4, 0
	v_dot8_i32_i4 v176, v84, v5, 0
	v_dot8_i32_i4 v177, v82, v4, 0
	v_dot8_i32_i4 v178, v82, v5, 0
	v_dot8_i32_i4 v133, v85, v6, v133
	v_dot8_i32_i4 v176, v85, v7, v176
	v_dot8_i32_i4 v177, v83, v6, v177
	v_dot8_i32_i4 v178, v83, v7, v178
	v_lshl_add_u32 v27, v12, 4, v27
	v_lshl_add_u32 v131, v131, 4, v132
	v_lshl_add_u32 v132, v133, 4, v176
	v_lshl_add_u32 v133, v177, 4, v178
	v_cndmask_b32_e64 v12, v132, v27, s[0:1]
	v_cndmask_b32_e64 v27, v27, v132, s[0:1]
	s_waitcnt lgkmcnt(0)
	v_lshl_add_u32 v140, v140, 9, v136
	v_add_u32_dpp v12, v27, v12 quad_perm:[1,0,3,2] row_mask:0xf bank_mask:0xf bound_ctrl:1
	v_cndmask_b32_e64 v27, v133, v131, s[0:1]
	v_cndmask_b32_e64 v131, v131, v133, s[0:1]
	v_lshl_add_u32 v141, v141, 9, v136
	v_lshl_add_u32 v142, v142, 9, v136
	v_add_u32_dpp v27, v131, v27 quad_perm:[1,0,3,2] row_mask:0xf bank_mask:0xf bound_ctrl:1
	v_cndmask_b32_e64 v131, v27, v12, s[2:3]
	v_cndmask_b32_e64 v12, v12, v27, s[2:3]
	v_lshl_add_u32 v143, v143, 9, v136
	global_load_dwordx2 v[80:81], v140, s[50:51]
	v_add_u32_dpp v12, v12, v131 quad_perm:[2,3,0,1] row_mask:0xf bank_mask:0xf bound_ctrl:1
	global_load_dwordx2 v[74:75], v141, s[50:51]
	global_load_dwordx2 v[84:85], v142, s[50:51]
	v_add_u32_dpp v12, v12, v12 row_ror:4 row_mask:0xf bank_mask:0xf bound_ctrl:1
	global_load_dwordx2 v[82:83], v143, s[50:51]
	s_waitcnt vmcnt(15)
	v_add_u32_dpp v12, v12, v12 row_ror:8 row_mask:0xf bank_mask:0xf bound_ctrl:1
	v_mov_b32_e32 v27, v12
	v_cvt_scalef32_pk_f32_fp4 v[160:161], v72, 1.0
	v_cvt_scalef32_pk_f32_fp4 v[162:163], v72, 1.0 op_sel:[1,0,0]
	v_permlane16_swap_b32_e32 v12, v27
	v_add_u32_e32 v12, v12, v27
	v_mov_b32_e32 v27, v12
	v_cvt_scalef32_pk_f32_fp4 v[164:165], v72, 1.0 op_sel:[0,1,0]
	v_cvt_scalef32_pk_f32_fp4 v[166:167], v72, 1.0 op_sel:[1,1,0]
	v_permlane32_swap_b32_e32 v12, v27
	v_add_u32_e32 v12, v27, v12
	v_cvt_f32_i32_e32 v12, v12
	v_mul_f32_e32 v12, v77, v12
	v_fma_f32 v179, |v12|, s39, 1.0
	v_rcp_f32_e32 v179, v179
	v_cmp_gt_f32_e32 vcc, 0, v12
	v_fmamk_f32 v180, v179, 0x3f07dc22, v129
	v_fmaak_f32 v180, v179, v180, 0x3f35f0e3
	v_fmaak_f32 v180, v179, v180, 0xbe11a98e
	v_fmaak_f32 v180, v179, v180, 0x3e027906
	v_mul_f32_e32 v179, v179, v180
	v_mul_f32_e32 v180, v12, v12
	v_mul_f32_e32 v180, 0xbf38aa3b, v180
	v_exp_f32_e32 v180, v180
	v_cvt_scalef32_pk_f32_fp4 v[168:169], v73, 1.0
	v_mul_f32_e32 v179, v180, v179
	v_mul_f32_e32 v180, v12, v179
	v_fma_f32 v12, -v12, v179, v12
	v_cndmask_b32_e32 v12, v12, v180, vcc
	v_mul_f32_e32 v12, v76, v12
	ds_read2st64_b32 v[76:77], v135 offset1:6
	v_readlane_b32 s4, v12, 0
	v_cvt_scalef32_pk_f32_fp4 v[170:171], v73, 1.0 op_sel:[1,0,0]
	v_cvt_scalef32_pk_f32_fp4 v[172:173], v73, 1.0 op_sel:[0,1,0]
	v_cvt_scalef32_pk_f32_fp4 v[174:175], v73, 1.0 op_sel:[1,1,0]
	global_load_dwordx2 v[72:73], v140, s[52:53]
	v_pk_fma_f32 v[100:101], s[4:5], v[160:161], v[100:101] op_sel_hi:[0,1,1]
	v_pk_fma_f32 v[98:99], s[4:5], v[162:163], v[98:99] op_sel_hi:[0,1,1]
	v_pk_fma_f32 v[96:97], s[4:5], v[164:165], v[96:97] op_sel_hi:[0,1,1]
	v_pk_fma_f32 v[94:95], s[4:5], v[166:167], v[94:95] op_sel_hi:[0,1,1]
	v_pk_fma_f32 v[92:93], s[4:5], v[168:169], v[92:93] op_sel_hi:[0,1,1]
	v_pk_fma_f32 v[90:91], s[4:5], v[170:171], v[90:91] op_sel_hi:[0,1,1]
	v_pk_fma_f32 v[88:89], s[4:5], v[172:173], v[88:89] op_sel_hi:[0,1,1]
	v_pk_fma_f32 v[86:87], s[4:5], v[174:175], v[86:87] op_sel_hi:[0,1,1]
	s_waitcnt vmcnt(15)
	v_readlane_b32 s4, v12, 2
	v_cvt_scalef32_pk_f32_fp4 v[160:161], v70, 1.0
	v_cvt_scalef32_pk_f32_fp4 v[162:163], v70, 1.0 op_sel:[1,0,0]
	v_pk_fma_f32 v[100:101], s[4:5], v[160:161], v[100:101] op_sel_hi:[0,1,1]
	v_cvt_scalef32_pk_f32_fp4 v[164:165], v70, 1.0 op_sel:[0,1,0]
	v_pk_fma_f32 v[98:99], s[4:5], v[162:163], v[98:99] op_sel_hi:[0,1,1]
	v_cvt_scalef32_pk_f32_fp4 v[166:167], v70, 1.0 op_sel:[1,1,0]
	v_pk_fma_f32 v[96:97], s[4:5], v[164:165], v[96:97] op_sel_hi:[0,1,1]
	v_cvt_scalef32_pk_f32_fp4 v[168:169], v71, 1.0
	v_pk_fma_f32 v[94:95], s[4:5], v[166:167], v[94:95] op_sel_hi:[0,1,1]
	v_cvt_scalef32_pk_f32_fp4 v[170:171], v71, 1.0 op_sel:[1,0,0]
	v_pk_fma_f32 v[92:93], s[4:5], v[168:169], v[92:93] op_sel_hi:[0,1,1]
	v_cvt_scalef32_pk_f32_fp4 v[172:173], v71, 1.0 op_sel:[0,1,0]
	v_pk_fma_f32 v[90:91], s[4:5], v[170:171], v[90:91] op_sel_hi:[0,1,1]
	v_cvt_scalef32_pk_f32_fp4 v[174:175], v71, 1.0 op_sel:[1,1,0]
	v_pk_fma_f32 v[88:89], s[4:5], v[172:173], v[88:89] op_sel_hi:[0,1,1]
	v_pk_fma_f32 v[86:87], s[4:5], v[174:175], v[86:87] op_sel_hi:[0,1,1]
	global_load_dwordx2 v[70:71], v141, s[52:53]
	s_waitcnt vmcnt(15)
	v_readlane_b32 s4, v12, 1
	v_cvt_scalef32_pk_f32_fp4 v[160:161], v62, 1.0
	v_cvt_scalef32_pk_f32_fp4 v[162:163], v62, 1.0 op_sel:[1,0,0]
	v_pk_fma_f32 v[100:101], s[4:5], v[160:161], v[100:101] op_sel_hi:[0,1,1]
	v_cvt_scalef32_pk_f32_fp4 v[164:165], v62, 1.0 op_sel:[0,1,0]
	v_pk_fma_f32 v[98:99], s[4:5], v[162:163], v[98:99] op_sel_hi:[0,1,1]
	v_cvt_scalef32_pk_f32_fp4 v[166:167], v62, 1.0 op_sel:[1,1,0]
	v_pk_fma_f32 v[96:97], s[4:5], v[164:165], v[96:97] op_sel_hi:[0,1,1]
	v_cvt_scalef32_pk_f32_fp4 v[168:169], v63, 1.0
	v_pk_fma_f32 v[94:95], s[4:5], v[166:167], v[94:95] op_sel_hi:[0,1,1]
	v_cvt_scalef32_pk_f32_fp4 v[170:171], v63, 1.0 op_sel:[1,0,0]
	v_pk_fma_f32 v[92:93], s[4:5], v[168:169], v[92:93] op_sel_hi:[0,1,1]
	v_cvt_scalef32_pk_f32_fp4 v[172:173], v63, 1.0 op_sel:[0,1,0]
	v_pk_fma_f32 v[90:91], s[4:5], v[170:171], v[90:91] op_sel_hi:[0,1,1]
	v_cvt_scalef32_pk_f32_fp4 v[174:175], v63, 1.0 op_sel:[1,1,0]
	v_pk_fma_f32 v[88:89], s[4:5], v[172:173], v[88:89] op_sel_hi:[0,1,1]
	v_pk_fma_f32 v[86:87], s[4:5], v[174:175], v[86:87] op_sel_hi:[0,1,1]
	global_load_dwordx2 v[62:63], v142, s[52:53]
	s_waitcnt vmcnt(15)
; __device__ __forceinline__ void p3_dots(const u32x2 (&ur)[4], const unsigned* rec, int lane, int (&pt)[4]) {
;     const u32x4 qh = *(const u32x4*)(rec + 256 + lane * 4);
; #pragma unroll
;     for (int u = 0; u < 4; u++) {
;         const int w0 = (int)ur[u].x, w1 = (int)ur[u].y;
;         int dh = __builtin_amdgcn_sdot8(w0, (int)qh.x, 0, false);
;         dh = __builtin_amdgcn_sdot8(w1, (int)qh.z, dh, false);
;         int dl = __builtin_amdgcn_sdot8(w0, (int)qh.y, 0, false);
;         dl = __builtin_amdgcn_sdot8(w1, (int)qh.w, dl, false);
;         pt[u] = (dh << 4) + dl;
;     }
; }
; template <int CTRL> __device__ __forceinline__ int dpp_i(int v) { return __builtin_amdgcn_mov_dpp(v, CTRL, 0xF, 0xF, true); }
; __device__ __forceinline__ int xrow_sum_i(int v) {
;     const auto a = __builtin_amdgcn_permlane16_swap((unsigned)v, (unsigned)v, false, false);
;     v = (int)a[0] + (int)a[1];
;     const auto b = __builtin_amdgcn_permlane32_swap((unsigned)v, (unsigned)v, false, false);
;     return (int)b[0] + (int)b[1];
; }
; __device__ __forceinline__ float p3_weight(const int (&pt)[4], int lane, float sh, int hs8, const P3Sc& sc) {
;     int m2[2], m1;
;     const bool c0 = lane & 1;
; #pragma unroll
;     for (int j = 0; j < 2; j++) { const int keep = c0 ? pt[j + 2] : pt[j], send = c0 ? pt[j] : pt[j + 2]; m2[j] = keep + dpp_i<0xB1>(send); }
;     const bool c1 = lane & 2;
;     { const int keep = c1 ? m2[1] : m2[0], send = c1 ? m2[0] : m2[1]; m1 = keep + dpp_i<0x4E>(send); }
;     m1 += dpp_i<0x124>(m1);
;     m1 += dpp_i<0x128>(m1);
;     m1 = xrow_sum_i(m1);
;     const float aval = (float)(m1 - hs8) * sc.su;
;     return sc.gm * gelu_erf(aval);
; }
; __device__ __forceinline__ void p3_axpy(const u32x2 (&vr)[4], float ws, f32x2 (&acc)[8]) {
; #pragma unroll
;     for (int u = 0; u < 4; u++) {
;         const int la = ((u >> 1) & 1) | ((u & 1) << 1);
;         const float wu = __builtin_bit_cast(float, __builtin_amdgcn_readlane(__builtin_bit_cast(int, ws), la));
;         const f32x2 w2 = {wu, wu};
;         const unsigned vw[2] = {vr[u].x, vr[u].y};
; #pragma unroll
;         for (int i = 0; i < 2; i++) {
;             acc[i * 4 + 0] = __builtin_elementwise_fma(w2, __builtin_amdgcn_cvt_scalef32_pk_f32_fp4(vw[i], 1.0f, 0), acc[i * 4 + 0]);
	v_readlane_b32 s4, v12, 3
	v_cvt_scalef32_pk_f32_fp4 v[160:161], v58, 1.0
	v_cvt_scalef32_pk_f32_fp4 v[162:163], v58, 1.0 op_sel:[1,0,0]
	v_pk_fma_f32 v[100:101], s[4:5], v[160:161], v[100:101] op_sel_hi:[0,1,1]
	v_cvt_scalef32_pk_f32_fp4 v[164:165], v58, 1.0 op_sel:[0,1,0]
	v_pk_fma_f32 v[98:99], s[4:5], v[162:163], v[98:99] op_sel_hi:[0,1,1]
	v_cvt_scalef32_pk_f32_fp4 v[166:167], v58, 1.0 op_sel:[1,1,0]
	v_pk_fma_f32 v[96:97], s[4:5], v[164:165], v[96:97] op_sel_hi:[0,1,1]
	v_cvt_scalef32_pk_f32_fp4 v[168:169], v59, 1.0
	v_pk_fma_f32 v[94:95], s[4:5], v[166:167], v[94:95] op_sel_hi:[0,1,1]
	v_cvt_scalef32_pk_f32_fp4 v[170:171], v59, 1.0 op_sel:[1,0,0]
	v_pk_fma_f32 v[92:93], s[4:5], v[168:169], v[92:93] op_sel_hi:[0,1,1]
	v_cvt_scalef32_pk_f32_fp4 v[172:173], v59, 1.0 op_sel:[0,1,0]
	v_pk_fma_f32 v[90:91], s[4:5], v[170:171], v[90:91] op_sel_hi:[0,1,1]
	v_cvt_scalef32_pk_f32_fp4 v[174:175], v59, 1.0 op_sel:[1,1,0]
	v_pk_fma_f32 v[88:89], s[4:5], v[172:173], v[88:89] op_sel_hi:[0,1,1]
	v_pk_fma_f32 v[86:87], s[4:5], v[174:175], v[86:87] op_sel_hi:[0,1,1]
	global_load_dwordx2 v[58:59], v143, s[52:53]
	ds_read_b128 v[144:147], v134 offset:2560
	s_waitcnt vmcnt(12) lgkmcnt(1)
	v_dot8_i32_i4 v12, v66, v0, 0
	v_dot8_i32_i4 v27, v66, v1, 0
	v_dot8_i32_i4 v131, v60, v0, 0
	v_dot8_i32_i4 v132, v60, v1, 0
	v_dot8_i32_i4 v12, v67, v2, v12
	v_dot8_i32_i4 v27, v67, v3, v27
	v_dot8_i32_i4 v131, v61, v2, v131
	v_dot8_i32_i4 v132, v61, v3, v132
	v_dot8_i32_i4 v133, v68, v0, 0
	v_dot8_i32_i4 v176, v68, v1, 0
	v_dot8_i32_i4 v177, v64, v0, 0
	v_dot8_i32_i4 v178, v64, v1, 0
	v_dot8_i32_i4 v133, v69, v2, v133
	v_dot8_i32_i4 v176, v69, v3, v176
	v_dot8_i32_i4 v177, v65, v2, v177
	v_dot8_i32_i4 v178, v65, v3, v178
	v_lshl_add_u32 v27, v12, 4, v27
	v_lshl_add_u32 v131, v131, 4, v132
	v_lshl_add_u32 v132, v133, 4, v176
	v_lshl_add_u32 v133, v177, 4, v178
	v_cndmask_b32_e64 v12, v132, v27, s[0:1]
	v_cndmask_b32_e64 v27, v27, v132, s[0:1]
	s_waitcnt lgkmcnt(0)
	v_lshl_add_u32 v144, v144, 9, v136
	v_add_u32_dpp v12, v27, v12 quad_perm:[1,0,3,2] row_mask:0xf bank_mask:0xf bound_ctrl:1
	v_cndmask_b32_e64 v27, v133, v131, s[0:1]
	v_cndmask_b32_e64 v131, v131, v133, s[0:1]
	v_lshl_add_u32 v145, v145, 9, v136
	v_lshl_add_u32 v146, v146, 9, v136
	v_add_u32_dpp v27, v131, v27 quad_perm:[1,0,3,2] row_mask:0xf bank_mask:0xf bound_ctrl:1
	v_cndmask_b32_e64 v131, v27, v12, s[2:3]
	v_cndmask_b32_e64 v12, v12, v27, s[2:3]
	v_lshl_add_u32 v147, v147, 9, v136
	global_load_dwordx2 v[66:67], v144, s[50:51]
	v_add_u32_dpp v12, v12, v131 quad_perm:[2,3,0,1] row_mask:0xf bank_mask:0xf bound_ctrl:1
	global_load_dwordx2 v[60:61], v145, s[50:51]
	global_load_dwordx2 v[68:69], v146, s[50:51]
	v_add_u32_dpp v12, v12, v12 row_ror:4 row_mask:0xf bank_mask:0xf bound_ctrl:1
	global_load_dwordx2 v[64:65], v147, s[50:51]
	s_waitcnt vmcnt(15)
	v_add_u32_dpp v12, v12, v12 row_ror:8 row_mask:0xf bank_mask:0xf bound_ctrl:1
	v_mov_b32_e32 v27, v12
	v_cvt_scalef32_pk_f32_fp4 v[160:161], v40, 1.0
	v_cvt_scalef32_pk_f32_fp4 v[162:163], v40, 1.0 op_sel:[1,0,0]
	v_permlane16_swap_b32_e32 v12, v27
	v_add_u32_e32 v12, v12, v27
	v_mov_b32_e32 v27, v12
	v_cvt_scalef32_pk_f32_fp4 v[164:165], v40, 1.0 op_sel:[0,1,0]
	v_cvt_scalef32_pk_f32_fp4 v[166:167], v40, 1.0 op_sel:[1,1,0]
	v_permlane32_swap_b32_e32 v12, v27
	v_add_u32_e32 v12, v27, v12
	v_cvt_f32_i32_e32 v12, v12
	v_mul_f32_e32 v12, v79, v12
	v_fma_f32 v179, |v12|, s39, 1.0
	v_rcp_f32_e32 v179, v179
	v_cmp_gt_f32_e32 vcc, 0, v12
	v_fmamk_f32 v180, v179, 0x3f07dc22, v129
	v_fmaak_f32 v180, v179, v180, 0x3f35f0e3
	v_fmaak_f32 v180, v179, v180, 0xbe11a98e
	v_fmaak_f32 v180, v179, v180, 0x3e027906
	v_mul_f32_e32 v179, v179, v180
	v_mul_f32_e32 v180, v12, v12
	v_mul_f32_e32 v180, 0xbf38aa3b, v180
	v_exp_f32_e32 v180, v180
	v_cvt_scalef32_pk_f32_fp4 v[168:169], v41, 1.0
	v_mul_f32_e32 v179, v180, v179
	v_mul_f32_e32 v180, v12, v179
	v_fma_f32 v12, -v12, v179, v12
	v_cndmask_b32_e32 v12, v12, v180, vcc
	v_mul_f32_e32 v12, v78, v12
	ds_read2st64_b32 v[78:79], v135 offset0:10 offset1:16
	v_readlane_b32 s4, v12, 0
	v_cvt_scalef32_pk_f32_fp4 v[170:171], v41, 1.0 op_sel:[1,0,0]
	v_cvt_scalef32_pk_f32_fp4 v[172:173], v41, 1.0 op_sel:[0,1,0]
	v_cvt_scalef32_pk_f32_fp4 v[174:175], v41, 1.0 op_sel:[1,1,0]
	global_load_dwordx2 v[40:41], v144, s[52:53]
	v_pk_fma_f32 v[52:53], s[4:5], v[160:161], v[52:53] op_sel_hi:[0,1,1]
	v_pk_fma_f32 v[50:51], s[4:5], v[162:163], v[50:51] op_sel_hi:[0,1,1]
	v_pk_fma_f32 v[48:49], s[4:5], v[164:165], v[48:49] op_sel_hi:[0,1,1]
	v_pk_fma_f32 v[46:47], s[4:5], v[166:167], v[46:47] op_sel_hi:[0,1,1]
	v_pk_fma_f32 v[44:45], s[4:5], v[168:169], v[44:45] op_sel_hi:[0,1,1]
	v_pk_fma_f32 v[42:43], s[4:5], v[170:171], v[42:43] op_sel_hi:[0,1,1]
	v_pk_fma_f32 v[54:55], s[4:5], v[172:173], v[54:55] op_sel_hi:[0,1,1]
	v_pk_fma_f32 v[56:57], s[4:5], v[174:175], v[56:57] op_sel_hi:[0,1,1]
	s_waitcnt vmcnt(15)
	v_readlane_b32 s4, v12, 2
	v_cvt_scalef32_pk_f32_fp4 v[160:161], v38, 1.0
	v_cvt_scalef32_pk_f32_fp4 v[162:163], v38, 1.0 op_sel:[1,0,0]
	v_pk_fma_f32 v[52:53], s[4:5], v[160:161], v[52:53] op_sel_hi:[0,1,1]
	v_cvt_scalef32_pk_f32_fp4 v[164:165], v38, 1.0 op_sel:[0,1,0]
	v_pk_fma_f32 v[50:51], s[4:5], v[162:163], v[50:51] op_sel_hi:[0,1,1]
	v_cvt_scalef32_pk_f32_fp4 v[166:167], v38, 1.0 op_sel:[1,1,0]
	v_pk_fma_f32 v[48:49], s[4:5], v[164:165], v[48:49] op_sel_hi:[0,1,1]
	v_cvt_scalef32_pk_f32_fp4 v[168:169], v39, 1.0
	v_pk_fma_f32 v[46:47], s[4:5], v[166:167], v[46:47] op_sel_hi:[0,1,1]
	v_cvt_scalef32_pk_f32_fp4 v[170:171], v39, 1.0 op_sel:[1,0,0]
	v_pk_fma_f32 v[44:45], s[4:5], v[168:169], v[44:45] op_sel_hi:[0,1,1]
	v_cvt_scalef32_pk_f32_fp4 v[172:173], v39, 1.0 op_sel:[0,1,0]
	v_pk_fma_f32 v[42:43], s[4:5], v[170:171], v[42:43] op_sel_hi:[0,1,1]
	v_cvt_scalef32_pk_f32_fp4 v[174:175], v39, 1.0 op_sel:[1,1,0]
	v_pk_fma_f32 v[54:55], s[4:5], v[172:173], v[54:55] op_sel_hi:[0,1,1]
	v_pk_fma_f32 v[56:57], s[4:5], v[174:175], v[56:57] op_sel_hi:[0,1,1]
	global_load_dwordx2 v[38:39], v145, s[52:53]
	s_waitcnt vmcnt(15)
; __device__ __forceinline__ void p3_axpy(const u32x2 (&vr)[4], float ws, f32x2 (&acc)[8]) {
; #pragma unroll
;     for (int u = 0; u < 4; u++) {
;         const int la = ((u >> 1) & 1) | ((u & 1) << 1);
;         const float wu = __builtin_bit_cast(float, __builtin_amdgcn_readlane(__builtin_bit_cast(int, ws), la));
;         const f32x2 w2 = {wu, wu};
;         const unsigned vw[2] = {vr[u].x, vr[u].y};
; #pragma unroll
;         for (int i = 0; i < 2; i++) {
;             acc[i * 4 + 0] = __builtin_elementwise_fma(w2, __builtin_amdgcn_cvt_scalef32_pk_f32_fp4(vw[i], 1.0f, 0), acc[i * 4 + 0]);
;             acc[i * 4 + 1] = __builtin_elementwise_fma(w2, __builtin_amdgcn_cvt_scalef32_pk_f32_fp4(vw[i], 1.0f, 1), acc[i * 4 + 1]);
;             acc[i * 4 + 2] = __builtin_elementwise_fma(w2, __builtin_amdgcn_cvt_scalef32_pk_f32_fp4(vw[i], 1.0f, 2), acc[i * 4 + 2]);
;             acc[i * 4 + 3] = __builtin_elementwise_fma(w2, __builtin_amdgcn_cvt_scalef32_pk_f32_fp4(vw[i], 1.0f, 3), acc[i * 4 + 3]);
;         }
;     }
; }
; __device__ void phaseP3(const Params& p, float* dstp, char* lds) {
;     ...
;         for (int g = 0; g < 32; g++) {
; #pragma unroll
;             for (int k = 0; k < TPW; k++) {
;                 int pt[4];
;                 p3_dots(ur[k], recs + k * (P3_REC / 4), lane, pt);
;                 const P3Sc sck = sc[k];
;                 if (g + 1 < 32) p3_load_u(ur[k], sc[k], UQ, tsc, lane, ul, g + 1, recs + k * (P3_REC / 4));
;                 const float w = p3_weight(pt, lane, sh[k], hs8[k], sck);
;                 p3_axpy(vr[k], w, acc[k]);
;                 if (g + 1 < 32) p3_load_v(vr[k], VQ, lane, g + 1, recs + k * (P3_REC / 4));
;             }
;         }
	v_readlane_b32 s4, v12, 1
	v_cvt_scalef32_pk_f32_fp4 v[160:161], v36, 1.0
	v_cvt_scalef32_pk_f32_fp4 v[162:163], v36, 1.0 op_sel:[1,0,0]
	v_pk_fma_f32 v[52:53], s[4:5], v[160:161], v[52:53] op_sel_hi:[0,1,1]
	v_cvt_scalef32_pk_f32_fp4 v[164:165], v36, 1.0 op_sel:[0,1,0]
	v_pk_fma_f32 v[50:51], s[4:5], v[162:163], v[50:51] op_sel_hi:[0,1,1]
	v_cvt_scalef32_pk_f32_fp4 v[166:167], v36, 1.0 op_sel:[1,1,0]
	v_pk_fma_f32 v[48:49], s[4:5], v[164:165], v[48:49] op_sel_hi:[0,1,1]
	v_cvt_scalef32_pk_f32_fp4 v[168:169], v37, 1.0
	v_pk_fma_f32 v[46:47], s[4:5], v[166:167], v[46:47] op_sel_hi:[0,1,1]
	v_cvt_scalef32_pk_f32_fp4 v[170:171], v37, 1.0 op_sel:[1,0,0]
	v_pk_fma_f32 v[44:45], s[4:5], v[168:169], v[44:45] op_sel_hi:[0,1,1]
	v_cvt_scalef32_pk_f32_fp4 v[172:173], v37, 1.0 op_sel:[0,1,0]
	v_pk_fma_f32 v[42:43], s[4:5], v[170:171], v[42:43] op_sel_hi:[0,1,1]
	v_cvt_scalef32_pk_f32_fp4 v[174:175], v37, 1.0 op_sel:[1,1,0]
	v_pk_fma_f32 v[54:55], s[4:5], v[172:173], v[54:55] op_sel_hi:[0,1,1]
	v_pk_fma_f32 v[56:57], s[4:5], v[174:175], v[56:57] op_sel_hi:[0,1,1]
	global_load_dwordx2 v[36:37], v146, s[52:53]
	s_waitcnt vmcnt(15)
	v_readlane_b32 s4, v12, 3
	v_cvt_scalef32_pk_f32_fp4 v[160:161], v34, 1.0
	v_cvt_scalef32_pk_f32_fp4 v[162:163], v34, 1.0 op_sel:[1,0,0]
	v_pk_fma_f32 v[52:53], s[4:5], v[160:161], v[52:53] op_sel_hi:[0,1,1]
	v_cvt_scalef32_pk_f32_fp4 v[164:165], v34, 1.0 op_sel:[0,1,0]
	v_pk_fma_f32 v[50:51], s[4:5], v[162:163], v[50:51] op_sel_hi:[0,1,1]
	v_cvt_scalef32_pk_f32_fp4 v[166:167], v34, 1.0 op_sel:[1,1,0]
	v_pk_fma_f32 v[48:49], s[4:5], v[164:165], v[48:49] op_sel_hi:[0,1,1]
	v_cvt_scalef32_pk_f32_fp4 v[168:169], v35, 1.0
	v_pk_fma_f32 v[46:47], s[4:5], v[166:167], v[46:47] op_sel_hi:[0,1,1]
	v_cvt_scalef32_pk_f32_fp4 v[170:171], v35, 1.0 op_sel:[1,0,0]
	v_pk_fma_f32 v[44:45], s[4:5], v[168:169], v[44:45] op_sel_hi:[0,1,1]
	v_cvt_scalef32_pk_f32_fp4 v[172:173], v35, 1.0 op_sel:[0,1,0]
	v_pk_fma_f32 v[42:43], s[4:5], v[170:171], v[42:43] op_sel_hi:[0,1,1]
	v_cvt_scalef32_pk_f32_fp4 v[174:175], v35, 1.0 op_sel:[1,1,0]
	v_pk_fma_f32 v[54:55], s[4:5], v[172:173], v[54:55] op_sel_hi:[0,1,1]
	v_pk_fma_f32 v[56:57], s[4:5], v[174:175], v[56:57] op_sel_hi:[0,1,1]
	global_load_dwordx2 v[34:35], v147, s[52:53]
	s_add_i32 s5, s5, 16
	s_cmpk_eq_i32 s5, 0x1f0
	s_cbranch_scc0 .LBB0_1075
	s_waitcnt vmcnt(0) lgkmcnt(0)
	v_mov_b32_e32 v104, v76
	v_mov_b32_e32 v105, v77
	v_mov_b32_e32 v102, v78
	v_mov_b32_e32 v103, v79
	v_mov_b32_e32 v12, v13
	v_mov_b32_e32 v27, v13
	s_waitcnt vmcnt(8)
	v_dot8c_i32_i4_e32 v12, v82, v4
	v_dot8c_i32_i4_e32 v27, v82, v5
	v_dot8c_i32_i4_e32 v12, v83, v6
	v_dot8c_i32_i4_e32 v27, v83, v7
	v_mov_b32_e32 v76, v13
	v_dot8c_i32_i4_e32 v76, v84, v5
	v_dot8c_i32_i4_e32 v76, v85, v7
	v_lshl_add_u32 v12, v12, 4, v27
	v_mov_b32_e32 v27, v13
	v_dot8c_i32_i4_e32 v27, v84, v4
	v_dot8c_i32_i4_e32 v27, v85, v6
	v_mov_b32_e32 v77, v13
	v_dot8c_i32_i4_e32 v77, v74, v5
	v_dot8c_i32_i4_e32 v77, v75, v7
	v_lshl_add_u32 v27, v27, 4, v76
	v_mov_b32_e32 v76, v13
	v_dot8c_i32_i4_e32 v76, v74, v4
	v_dot8c_i32_i4_e32 v76, v75, v6
	v_mov_b32_e32 v75, v13
	v_dot8c_i32_i4_e32 v75, v80, v4
	v_mov_b32_e32 v4, v13
	v_dot8c_i32_i4_e32 v4, v80, v5
	v_dot8c_i32_i4_e32 v75, v81, v6
	v_dot8c_i32_i4_e32 v4, v81, v7
	v_lshl_add_u32 v74, v76, 4, v77
	v_cndmask_b32_e64 v6, v74, v12, s[0:1]
	v_cvt_scalef32_pk_f32_fp4 v[76:77], v72, 1.0 op_sel:[1,1,0]
	v_lshl_add_u32 v4, v75, 4, v4
	v_cndmask_b32_e64 v5, v27, v4, s[0:1]
	v_cndmask_b32_e64 v4, v4, v27, s[0:1]
	v_cvt_scalef32_pk_f32_fp4 v[78:79], v73, 1.0
	v_cvt_scalef32_pk_f32_fp4 v[80:81], v73, 1.0 op_sel:[1,0,0]
	v_add_u32_dpp v4, v4, v5 quad_perm:[1,0,3,2] row_mask:0xf bank_mask:0xf bound_ctrl:1
	v_cndmask_b32_e64 v5, v12, v74, s[0:1]
	v_cvt_scalef32_pk_f32_fp4 v[74:75], v72, 1.0 op_sel:[0,1,0]
	v_cvt_scalef32_pk_f32_fp4 v[82:83], v73, 1.0 op_sel:[0,1,0]
	v_add_u32_dpp v5, v6, v5 quad_perm:[1,0,3,2] row_mask:0xf bank_mask:0xf bound_ctrl:1
	v_cndmask_b32_e64 v6, v5, v4, s[2:3]
	v_cndmask_b32_e64 v4, v4, v5, s[2:3]
	v_cvt_scalef32_pk_f32_fp4 v[84:85], v70, 1.0
	v_lshl_add_u64 v[28:29], v[22:23], 0, v[28:29]
	v_add_u32_dpp v4, v4, v6 quad_perm:[2,3,0,1] row_mask:0xf bank_mask:0xf bound_ctrl:1
	v_mov_b32_e32 v27, v13
	v_cvt_scalef32_pk_f32_fp4 v[108:109], v62, 1.0 op_sel:[0,1,0]
	v_add_u32_dpp v4, v4, v4 row_ror:4 row_mask:0xf bank_mask:0xf bound_ctrl:1
	s_nop 1
	v_add_u32_dpp v4, v4, v4 row_ror:8 row_mask:0xf bank_mask:0xf bound_ctrl:1
	v_mov_b32_e32 v5, v4
	s_nop 1
	v_permlane16_swap_b32_e32 v4, v5
	v_add_u32_e32 v4, v4, v5
	v_mov_b32_e32 v5, v4
	s_nop 1
	v_permlane32_swap_b32_e32 v4, v5
	v_add_u32_e32 v4, v5, v4
	v_cvt_f32_i32_e32 v4, v4
	v_mul_f32_e32 v4, v105, v4
	v_fma_f32 v5, |v4|, s39, 1.0
	v_rcp_f32_e32 v5, v5
	v_mul_f32_e32 v7, v4, v4
	v_mul_f32_e32 v7, 0xbf38aa3b, v7
	v_exp_f32_e32 v7, v7
	v_fmamk_f32 v6, v5, 0x3f07dc22, v129
	v_fmaak_f32 v6, v5, v6, 0x3f35f0e3
	v_fmaak_f32 v6, v5, v6, 0xbe11a98e
	v_fmaak_f32 v6, v5, v6, 0x3e027906
	v_mul_f32_e32 v5, v5, v6
	v_mul_f32_e32 v5, v7, v5
	v_mul_f32_e32 v6, v4, v5
	v_fma_f32 v5, -v4, v5, v4
	v_cmp_gt_f32_e32 vcc, 0, v4
	s_nop 1
	v_cndmask_b32_e32 v4, v5, v6, vcc
	v_mul_f32_e32 v12, v104, v4
	v_cvt_scalef32_pk_f32_fp4 v[4:5], v72, 1.0
	v_readlane_b32 s4, v12, 0
	v_cvt_scalef32_pk_f32_fp4 v[6:7], v72, 1.0 op_sel:[1,0,0]
	v_cvt_scalef32_pk_f32_fp4 v[72:73], v73, 1.0 op_sel:[1,1,0]
	v_pk_fma_f32 v[4:5], s[4:5], v[4:5], v[100:101] op_sel_hi:[0,1,1]
	v_pk_fma_f32 v[6:7], s[4:5], v[6:7], v[98:99] op_sel_hi:[0,1,1]
	v_pk_fma_f32 v[74:75], s[4:5], v[74:75], v[96:97] op_sel_hi:[0,1,1]
	v_pk_fma_f32 v[76:77], s[4:5], v[76:77], v[94:95] op_sel_hi:[0,1,1]
; __device__ __forceinline__ void p3_dots(const u32x2 (&ur)[4], const unsigned* rec, int lane, int (&pt)[4]) {
;     const u32x4 qh = *(const u32x4*)(rec + 256 + lane * 4);
; #pragma unroll
;     for (int u = 0; u < 4; u++) {
;         const int w0 = (int)ur[u].x, w1 = (int)ur[u].y;
;         int dh = __builtin_amdgcn_sdot8(w0, (int)qh.x, 0, false);
;         dh = __builtin_amdgcn_sdot8(w1, (int)qh.z, dh, false);
;         int dl = __builtin_amdgcn_sdot8(w0, (int)qh.y, 0, false);
;         dl = __builtin_amdgcn_sdot8(w1, (int)qh.w, dl, false);
;         pt[u] = (dh << 4) + dl;
;     }
; }
; template <int CTRL> __device__ __forceinline__ int dpp_i(int v) { return __builtin_amdgcn_mov_dpp(v, CTRL, 0xF, 0xF, true); }
; __device__ __forceinline__ int xrow_sum_i(int v) {
;     const auto a = __builtin_amdgcn_permlane16_swap((unsigned)v, (unsigned)v, false, false);
;     v = (int)a[0] + (int)a[1];
;     const auto b = __builtin_amdgcn_permlane32_swap((unsigned)v, (unsigned)v, false, false);
;     return (int)b[0] + (int)b[1];
; }
; __device__ __forceinline__ float p3_weight(const int (&pt)[4], int lane, float sh, int hs8, const P3Sc& sc) {
;     int m2[2], m1;
;     const bool c0 = lane & 1;
; #pragma unroll
;     for (int j = 0; j < 2; j++) { const int keep = c0 ? pt[j + 2] : pt[j], send = c0 ? pt[j] : pt[j + 2]; m2[j] = keep + dpp_i<0xB1>(send); }
;     const bool c1 = lane & 2;
;     { const int keep = c1 ? m2[1] : m2[0], send = c1 ? m2[0] : m2[1]; m1 = keep + dpp_i<0x4E>(send); }
;     m1 += dpp_i<0x124>(m1);
;     m1 += dpp_i<0x128>(m1);
;     m1 = xrow_sum_i(m1);
;     const float aval = (float)(m1 - hs8) * sc.su;
;     return sc.gm * gelu_erf(aval);
; }
; __device__ __forceinline__ void p3_axpy(const u32x2 (&vr)[4], float ws, f32x2 (&acc)[8]) {
; #pragma unroll
;     for (int u = 0; u < 4; u++) {
;         const int la = ((u >> 1) & 1) | ((u & 1) << 1);
;         const float wu = __builtin_bit_cast(float, __builtin_amdgcn_readlane(__builtin_bit_cast(int, ws), la));
;         const f32x2 w2 = {wu, wu};
;         const unsigned vw[2] = {vr[u].x, vr[u].y};
; #pragma unroll
;         for (int i = 0; i < 2; i++) {
;             acc[i * 4 + 0] = __builtin_elementwise_fma(w2, __builtin_amdgcn_cvt_scalef32_pk_f32_fp4(vw[i], 1.0f, 0), acc[i * 4 + 0]);
	v_pk_fma_f32 v[78:79], s[4:5], v[78:79], v[92:93] op_sel_hi:[0,1,1]
	v_pk_fma_f32 v[80:81], s[4:5], v[80:81], v[90:91] op_sel_hi:[0,1,1]
	v_pk_fma_f32 v[82:83], s[4:5], v[82:83], v[88:89] op_sel_hi:[0,1,1]
	v_pk_fma_f32 v[72:73], s[4:5], v[72:73], v[86:87] op_sel_hi:[0,1,1]
	v_readlane_b32 s4, v12, 2
	s_nop 1
	v_pk_fma_f32 v[4:5], s[4:5], v[84:85], v[4:5] op_sel_hi:[0,1,1]
	v_cvt_scalef32_pk_f32_fp4 v[84:85], v70, 1.0 op_sel:[1,0,0]
	v_pk_fma_f32 v[84:85], s[4:5], v[84:85], v[6:7] op_sel_hi:[0,1,1]
	v_cvt_scalef32_pk_f32_fp4 v[6:7], v70, 1.0 op_sel:[0,1,0]
	v_pk_fma_f32 v[90:91], s[4:5], v[6:7], v[74:75] op_sel_hi:[0,1,1]
	v_cvt_scalef32_pk_f32_fp4 v[6:7], v70, 1.0 op_sel:[1,1,0]
	v_pk_fma_f32 v[92:93], s[4:5], v[6:7], v[76:77] op_sel_hi:[0,1,1]
	v_cvt_scalef32_pk_f32_fp4 v[6:7], v71, 1.0
	v_pk_fma_f32 v[94:95], s[4:5], v[6:7], v[78:79] op_sel_hi:[0,1,1]
	v_cvt_scalef32_pk_f32_fp4 v[6:7], v71, 1.0 op_sel:[1,0,0]
	v_pk_fma_f32 v[96:97], s[4:5], v[6:7], v[80:81] op_sel_hi:[0,1,1]
	v_cvt_scalef32_pk_f32_fp4 v[6:7], v71, 1.0 op_sel:[0,1,0]
	v_pk_fma_f32 v[98:99], s[4:5], v[6:7], v[82:83] op_sel_hi:[0,1,1]
	v_cvt_scalef32_pk_f32_fp4 v[6:7], v71, 1.0 op_sel:[1,1,0]
	v_pk_fma_f32 v[100:101], s[4:5], v[6:7], v[72:73] op_sel_hi:[0,1,1]
	v_ashrrev_i32_e32 v6, 11, v8
	v_mul_i32_i24_e32 v6, 0x1800, v6
	v_ashrrev_i32_e32 v7, 31, v6
	v_lshl_add_u64 v[6:7], v[6:7], 2, s[22:23]
	v_readlane_b32 s4, v12, 1
	global_load_dwordx4 v[70:73], v[28:29], off offset:16
	global_load_dwordx4 v[74:77], v[28:29], off
	v_lshl_add_u64 v[28:29], v[6:7], 0, v[26:27]
	v_cvt_scalef32_pk_f32_fp4 v[82:83], v62, 1.0
	v_add_co_u32_e32 v6, vcc, s40, v28
	v_pk_fma_f32 v[104:105], s[4:5], v[82:83], v[4:5] op_sel_hi:[0,1,1]
	v_cvt_scalef32_pk_f32_fp4 v[4:5], v62, 1.0 op_sel:[1,0,0]
	v_addc_co_u32_e32 v7, vcc, 0, v29, vcc
	v_pk_fma_f32 v[106:107], s[4:5], v[4:5], v[84:85] op_sel_hi:[0,1,1]
	v_lshl_add_u64 v[4:5], v[28:29], 0, s[30:31]
	v_pk_fma_f32 v[28:29], s[4:5], v[108:109], v[90:91] op_sel_hi:[0,1,1]
	v_cvt_scalef32_pk_f32_fp4 v[90:91], v62, 1.0 op_sel:[1,1,0]
	v_pk_fma_f32 v[108:109], s[4:5], v[90:91], v[92:93] op_sel_hi:[0,1,1]
	v_cvt_scalef32_pk_f32_fp4 v[90:91], v63, 1.0
	global_load_dwordx4 v[78:81], v[6:7], off
	v_pk_fma_f32 v[94:95], s[4:5], v[90:91], v[94:95] op_sel_hi:[0,1,1]
	v_cvt_scalef32_pk_f32_fp4 v[90:91], v63, 1.0 op_sel:[1,0,0]
	global_load_dwordx4 v[82:85], v[4:5], off offset:32
	global_load_dwordx4 v[86:89], v[4:5], off offset:16
	v_pk_fma_f32 v[96:97], s[4:5], v[90:91], v[96:97] op_sel_hi:[0,1,1]
	v_cvt_scalef32_pk_f32_fp4 v[90:91], v63, 1.0 op_sel:[0,1,0]
	v_cvt_scalef32_pk_f32_fp4 v[62:63], v63, 1.0 op_sel:[1,1,0]
	v_pk_fma_f32 v[98:99], s[4:5], v[90:91], v[98:99] op_sel_hi:[0,1,1]
	v_pk_fma_f32 v[62:63], s[4:5], v[62:63], v[100:101] op_sel_hi:[0,1,1]
	v_readlane_b32 s4, v12, 3
	s_waitcnt vmcnt(11)
	v_cvt_scalef32_pk_f32_fp4 v[90:91], v58, 1.0
	v_mov_b32_e32 v12, v13
	v_pk_fma_f32 v[100:101], s[4:5], v[90:91], v[104:105] op_sel_hi:[0,1,1]
	global_load_dwordx4 v[90:93], v[4:5], off offset:48
	v_cvt_scalef32_pk_f32_fp4 v[104:105], v58, 1.0 op_sel:[1,0,0]
	v_pk_fma_f32 v[104:105], s[4:5], v[104:105], v[106:107] op_sel_hi:[0,1,1]
	v_cvt_scalef32_pk_f32_fp4 v[106:107], v58, 1.0 op_sel:[0,1,0]
	v_pk_fma_f32 v[28:29], s[4:5], v[106:107], v[28:29] op_sel_hi:[0,1,1]
	v_cvt_scalef32_pk_f32_fp4 v[106:107], v58, 1.0 op_sel:[1,1,0]
	v_pk_fma_f32 v[106:107], s[4:5], v[106:107], v[108:109] op_sel_hi:[0,1,1]
	v_cvt_scalef32_pk_f32_fp4 v[108:109], v59, 1.0
	v_pk_fma_f32 v[94:95], s[4:5], v[108:109], v[94:95] op_sel_hi:[0,1,1]
	v_cvt_scalef32_pk_f32_fp4 v[108:109], v59, 1.0 op_sel:[1,0,0]
	s_waitcnt vmcnt(9)
	v_dot8c_i32_i4_e32 v12, v64, v0
	v_dot8c_i32_i4_e32 v27, v64, v1
	v_pk_fma_f32 v[96:97], s[4:5], v[108:109], v[96:97] op_sel_hi:[0,1,1]
	v_cvt_scalef32_pk_f32_fp4 v[108:109], v59, 1.0 op_sel:[0,1,0]
	v_cvt_scalef32_pk_f32_fp4 v[58:59], v59, 1.0 op_sel:[1,1,0]
	v_dot8c_i32_i4_e32 v12, v65, v2
	v_dot8c_i32_i4_e32 v27, v65, v3
	v_pk_fma_f32 v[98:99], s[4:5], v[108:109], v[98:99] op_sel_hi:[0,1,1]
	v_pk_fma_f32 v[108:109], s[4:5], v[58:59], v[62:63] op_sel_hi:[0,1,1]
	v_mov_b32_e32 v58, v13
	v_lshl_add_u32 v12, v12, 4, v27
	v_mov_b32_e32 v27, v13
	v_dot8c_i32_i4_e32 v27, v68, v0
	v_dot8c_i32_i4_e32 v58, v68, v1
	v_dot8c_i32_i4_e32 v27, v69, v2
	v_dot8c_i32_i4_e32 v58, v69, v3
	v_mov_b32_e32 v59, v13
	s_waitcnt vmcnt(7)
	v_dot8c_i32_i4_e32 v59, v60, v1
	v_dot8c_i32_i4_e32 v59, v61, v3
	v_lshl_add_u32 v27, v27, 4, v58
	v_mov_b32_e32 v58, v13
	v_dot8c_i32_i4_e32 v58, v60, v0
	v_dot8c_i32_i4_e32 v58, v61, v2
	s_waitcnt vmcnt(4)
	v_lshlrev_b32_e32 v110, 16, v74
	s_nop 0
	v_lshl_add_u32 v58, v58, 4, v59
	v_mov_b32_e32 v59, v13
	v_dot8c_i32_i4_e32 v59, v66, v0
	v_mov_b32_e32 v0, v13
	v_dot8c_i32_i4_e32 v0, v66, v1
	v_dot8c_i32_i4_e32 v59, v67, v2
	v_dot8c_i32_i4_e32 v0, v67, v3
	v_cndmask_b32_e64 v2, v58, v12, s[0:1]
	v_and_b32_e32 v111, 0xffff0000, v74
	v_lshlrev_b32_e32 v74, 16, v75
	v_lshl_add_u32 v0, v59, 4, v0
	v_cndmask_b32_e64 v1, v27, v0, s[0:1]
	v_cndmask_b32_e64 v0, v0, v27, s[0:1]
	v_and_b32_e32 v75, 0xffff0000, v75
	s_waitcnt vmcnt(3)
	v_pk_fma_f32 v[74:75], v[104:105], v[80:81], v[74:75]
	v_add_u32_dpp v0, v0, v1 quad_perm:[1,0,3,2] row_mask:0xf bank_mask:0xf bound_ctrl:1
	v_cndmask_b32_e64 v1, v12, v58, s[0:1]
	v_lshlrev_b32_e32 v104, 16, v76
	v_and_b32_e32 v105, 0xffff0000, v76
	v_add_u32_dpp v1, v2, v1 quad_perm:[1,0,3,2] row_mask:0xf bank_mask:0xf bound_ctrl:1
	v_cndmask_b32_e64 v12, v1, v0, s[2:3]
	v_cndmask_b32_e64 v27, v0, v1, s[2:3]
	global_load_dwordx4 v[0:3], v[24:25], off offset:48
	global_load_dwordx4 v[58:61], v[24:25], off offset:32
	global_load_dwordx4 v[62:65], v[24:25], off offset:16
	global_load_dwordx4 v[66:69], v[24:25], off
	v_pk_fma_f32 v[78:79], v[100:101], v[78:79], v[110:111]
	s_waitcnt vmcnt(5)
; __device__ __forceinline__ float bf_lo(unsigned u) { return __uint_as_float(u << 16); }
; __device__ __forceinline__ float bf_hi(unsigned u) { return __uint_as_float(u & 0xffff0000u); }
; __device__ __forceinline__ void p3_finish(const Params& p, float* dstp, int tok, int lane, const f32x2 (&acc)[8], float* tr) {
;     const float* mod = (const float*)(p.ws + OFF_MOD);
;     const int b = tok >> 11;
;     float own[16];
; #pragma unroll
;     for (int i = 0; i < 16; i++) own[i] = acc[i >> 1][i & 1];
;     const int d0 = lane * 16;
;     float x2[16];
;     float ss = 0.f;
;     const bf16_t* x1b = (const bf16_t*)(p.ws + OFF_X1B) + (size_t)tok * DM + d0;
;     const u32x4 xa = *(const u32x4*)x1b, xb = *(const u32x4*)(x1b + 8);
;     const unsigned xw[8] = {xa.x, xa.y, xa.z, xa.w, xb.x, xb.y, xb.z, xb.w};
; #pragma unroll
;     for (int i = 0; i < 4; i++) {
;         const int d = d0 + i * 4;
;         const f32x4 xv = {bf_lo(xw[2 * i]), bf_hi(xw[2 * i]), bf_lo(xw[2 * i + 1]), bf_hi(xw[2 * i + 1])};
;         const f32x4 gt = *(const f32x4*)(mod + b * 6144 + 5 * 1024 + d);
; #pragma unroll
;         for (int j = 0; j < 4; j++) { const float v = xv[j] + gt[j] * own[i * 4 + j]; x2[i * 4 + j] = v; ss += v * v; }
;     }
;     ss = wave_sum(ss);
;     const float rstd = rsqrtf(ss * (1.f / 1024.f) + 1e-6f);
; #pragma unroll
;     for (int i = 0; i < 4; i++) {
;         const int d = d0 + i * 4;
;         const f32x4 fg = *(const f32x4*)(p.final_g + d);
;         f32x4 o;
; #pragma unroll
;         for (int j = 0; j < 4; j++) o[j] = x2[i * 4 + j] * rstd * fg[j];
;         *(f32x4*)(tr + d) = o;
;     }
;     __builtin_amdgcn_fence(__ATOMIC_RELEASE, "wavefront");
;     __builtin_amdgcn_wave_barrier();
;     __builtin_amdgcn_fence(__ATOMIC_ACQUIRE, "wavefront");
; #pragma unroll
;     for (int j = 0; j < 4; j++) {
;         const f32x4 v = *(const f32x4*)(tr + j * 256 + lane * 4);
;         *(f32x4*)(dstp + (size_t)tok * DM + j * 256 + lane * 4) = v;
;     }
;     __builtin_amdgcn_wave_barrier();
; }
	v_pk_fma_f32 v[28:29], v[28:29], v[86:87], v[104:105]
	v_lshlrev_b32_e32 v104, 16, v70
	v_and_b32_e32 v105, 0xffff0000, v70
	v_lshlrev_b32_e32 v70, 16, v71
	v_and_b32_e32 v71, 0xffff0000, v71
	v_pk_mul_f32 v[100:101], v[78:79], v[78:79]
	v_pk_fma_f32 v[70:71], v[96:97], v[84:85], v[70:71]
	v_lshlrev_b32_e32 v96, 16, v72
	v_and_b32_e32 v97, 0xffff0000, v72
	v_pk_mul_f32 v[80:81], v[74:75], v[74:75]
	s_waitcnt vmcnt(4)
	v_pk_fma_f32 v[90:91], v[98:99], v[90:91], v[96:97]
	v_add_f32_e32 v98, v100, v101
	v_add_f32_e32 v80, v80, v98
	v_pk_mul_f32 v[86:87], v[28:29], v[28:29]
	v_lshlrev_b32_e32 v76, 16, v77
	v_and_b32_e32 v77, 0xffff0000, v77
	v_add_f32_e32 v80, v81, v80
	v_pk_fma_f32 v[76:77], v[106:107], v[88:89], v[76:77]
	v_add_f32_e32 v80, v86, v80
	v_pk_mul_f32 v[88:89], v[76:77], v[76:77]
	v_add_f32_e32 v80, v87, v80
	v_pk_fma_f32 v[82:83], v[94:95], v[82:83], v[104:105]
	v_add_f32_e32 v80, v88, v80
	v_pk_mul_f32 v[94:95], v[82:83], v[82:83]
	v_add_f32_e32 v80, v89, v80
	v_add_f32_e32 v80, v94, v80
	v_pk_mul_f32 v[84:85], v[70:71], v[70:71]
	v_add_f32_e32 v80, v95, v80
	v_add_f32_e32 v80, v84, v80
	v_pk_mul_f32 v[96:97], v[90:91], v[90:91]
	v_lshlrev_b32_e32 v72, 16, v73
	v_and_b32_e32 v73, 0xffff0000, v73
	v_add_f32_e32 v80, v85, v80
	v_pk_fma_f32 v[72:73], v[108:109], v[92:93], v[72:73]
	v_add_f32_e32 v80, v96, v80
	v_pk_mul_f32 v[92:93], v[72:73], v[72:73]
	v_add_f32_e32 v80, v97, v80
	v_add_f32_e32 v80, v92, v80
	v_add_f32_e32 v80, v93, v80
	ds_bpermute_b32 v81, v112, v80
	v_add_u32_dpp v12, v27, v12 quad_perm:[2,3,0,1] row_mask:0xf bank_mask:0xf bound_ctrl:1
	s_waitcnt lgkmcnt(0)
	v_add_f32_e32 v80, v80, v81
	ds_bpermute_b32 v81, v113, v80
	v_add_u32_dpp v12, v12, v12 row_ror:4 row_mask:0xf bank_mask:0xf bound_ctrl:1
	s_waitcnt lgkmcnt(0)
	v_add_f32_e32 v80, v80, v81
	v_add_u32_dpp v12, v12, v12 row_ror:8 row_mask:0xf bank_mask:0xf bound_ctrl:1
	v_mov_b32_e32 v27, v12
	ds_bpermute_b32 v81, v114, v80
	s_nop 0
	v_permlane16_swap_b32_e32 v12, v27
	v_add_u32_e32 v12, v12, v27
	v_mov_b32_e32 v27, v12
	s_nop 1
	v_permlane32_swap_b32_e32 v12, v27
	v_add_u32_e32 v12, v27, v12
	s_waitcnt lgkmcnt(0)
	v_add_f32_e32 v27, v80, v81
	ds_bpermute_b32 v80, v115, v27
	v_cvt_f32_i32_e32 v12, v12
	s_waitcnt lgkmcnt(0)
	v_add_f32_e32 v27, v27, v80
	ds_bpermute_b32 v80, v116, v27
	v_mul_f32_e32 v81, v103, v12
	v_fma_f32 v12, |v81|, s39, 1.0
	v_rcp_f32_e32 v12, v12
	s_waitcnt lgkmcnt(0)
	v_add_f32_e32 v27, v27, v80
	ds_bpermute_b32 v80, v117, v27
	v_fmamk_f32 v84, v12, 0x3f07dc22, v129
	v_fmaak_f32 v84, v12, v84, 0x3f35f0e3
	v_fmaak_f32 v84, v12, v84, 0xbe11a98e
	v_fmaak_f32 v84, v12, v84, 0x3e027906
	s_waitcnt lgkmcnt(0)
	v_add_f32_e32 v27, v27, v80
	v_mul_f32_e32 v12, v12, v84
	v_mul_f32_e32 v84, v81, v81
	v_fmamk_f32 v27, v27, 0x3a800000, v130
	v_mul_f32_e32 v84, 0xbf38aa3b, v84
	v_mul_f32_e32 v80, 0x4b800000, v27
	v_cmp_gt_f32_e32 vcc, s38, v27
	v_exp_f32_e32 v84, v84
	s_nop 0
	v_cndmask_b32_e32 v27, v27, v80, vcc
	v_rsq_f32_e32 v27, v27
	v_mul_f32_e32 v12, v84, v12
	v_mul_f32_e32 v80, v81, v12
	v_fma_f32 v84, -v81, v12, v81
	v_mul_f32_e32 v12, 0x45800000, v27
	v_cndmask_b32_e32 v12, v27, v12, vcc
	v_pk_mul_f32 v[78:79], v[78:79], v[12:13] op_sel_hi:[1,0]
	v_pk_mul_f32 v[74:75], v[74:75], v[12:13] op_sel_hi:[1,0]
	s_waitcnt vmcnt(0)
	v_pk_mul_f32 v[66:67], v[66:67], v[78:79]
	v_pk_mul_f32 v[68:69], v[68:69], v[74:75]
	ds_write_b128 v118, v[66:69]
	v_pk_mul_f32 v[28:29], v[28:29], v[12:13] op_sel_hi:[1,0]
	v_pk_mul_f32 v[66:67], v[76:77], v[12:13] op_sel_hi:[1,0]
	v_pk_mul_f32 v[62:63], v[62:63], v[28:29]
	v_pk_mul_f32 v[64:65], v[64:65], v[66:67]
	ds_write_b128 v118, v[62:65] offset:16
	v_pk_mul_f32 v[28:29], v[82:83], v[12:13] op_sel_hi:[1,0]
	v_pk_mul_f32 v[62:63], v[70:71], v[12:13] op_sel_hi:[1,0]
	v_pk_mul_f32 v[58:59], v[58:59], v[28:29]
	v_pk_mul_f32 v[60:61], v[60:61], v[62:63]
	ds_write_b128 v118, v[58:61] offset:32
	v_pk_mul_f32 v[28:29], v[90:91], v[12:13] op_sel_hi:[1,0]
	v_pk_mul_f32 v[58:59], v[72:73], v[12:13] op_sel_hi:[1,0]
	v_pk_mul_f32 v[0:1], v[0:1], v[28:29]
	v_pk_mul_f32 v[2:3], v[2:3], v[58:59]
	ds_write_b128 v118, v[0:3] offset:48
	ds_read_b128 v[0:3], v128
	ds_read_b128 v[58:61], v128 offset:1024
	ds_read_b128 v[62:65], v128 offset:2048
	ds_read_b128 v[66:69], v128 offset:3072
	v_lshlrev_b64 v[28:29], 12, v[8:9]
	v_lshl_add_u64 v[28:29], v[18:19], 0, v[28:29]
	s_waitcnt lgkmcnt(3)
	global_store_dwordx4 v[28:29], v[0:3], off
	s_waitcnt lgkmcnt(2)
	global_store_dwordx4 v[28:29], v[58:61], off offset:1024
	s_waitcnt lgkmcnt(1)
	global_store_dwordx4 v[28:29], v[62:65], off offset:2048
	s_waitcnt lgkmcnt(0)
	global_store_dwordx4 v[28:29], v[66:69], off offset:3072
	v_lshl_add_u64 v[28:29], v[22:23], 0, v[32:33]
	global_load_dwordx4 v[0:3], v[28:29], off offset:16
	global_load_dwordx4 v[58:61], v[28:29], off
	global_load_dwordx4 v[62:65], v[6:7], off
	v_cmp_gt_f32_e32 vcc, 0, v81
	global_load_dwordx4 v[66:69], v[4:5], off offset:32
	global_load_dwordx4 v[70:73], v[4:5], off offset:16
	v_cndmask_b32_e32 v6, v84, v80, vcc
	v_mul_f32_e32 v9, v102, v6
	v_cvt_scalef32_pk_f32_fp4 v[6:7], v40, 1.0
	v_readlane_b32 s4, v9, 0
	v_add_u32_e32 v8, s36, v8
	s_waitcnt vmcnt(3)
; __device__ __forceinline__ float bf_lo(unsigned u) { return __uint_as_float(u << 16); }
; __device__ __forceinline__ float bf_hi(unsigned u) { return __uint_as_float(u & 0xffff0000u); }
; __device__ __forceinline__ void p3_axpy(const u32x2 (&vr)[4], float ws, f32x2 (&acc)[8]) {
; #pragma unroll
;     for (int u = 0; u < 4; u++) {
;         const int la = ((u >> 1) & 1) | ((u & 1) << 1);
;         const float wu = __builtin_bit_cast(float, __builtin_amdgcn_readlane(__builtin_bit_cast(int, ws), la));
;         const f32x2 w2 = {wu, wu};
;         const unsigned vw[2] = {vr[u].x, vr[u].y};
; #pragma unroll
;         for (int i = 0; i < 2; i++) {
;             acc[i * 4 + 0] = __builtin_elementwise_fma(w2, __builtin_amdgcn_cvt_scalef32_pk_f32_fp4(vw[i], 1.0f, 0), acc[i * 4 + 0]);
;             acc[i * 4 + 1] = __builtin_elementwise_fma(w2, __builtin_amdgcn_cvt_scalef32_pk_f32_fp4(vw[i], 1.0f, 1), acc[i * 4 + 1]);
;             acc[i * 4 + 2] = __builtin_elementwise_fma(w2, __builtin_amdgcn_cvt_scalef32_pk_f32_fp4(vw[i], 1.0f, 2), acc[i * 4 + 2]);
;             acc[i * 4 + 3] = __builtin_elementwise_fma(w2, __builtin_amdgcn_cvt_scalef32_pk_f32_fp4(vw[i], 1.0f, 3), acc[i * 4 + 3]);
;         }
;     }
; }
; __device__ __forceinline__ void p3_finish(const Params& p, float* dstp, int tok, int lane, const f32x2 (&acc)[8], float* tr) {
;     ...
;     const bf16_t* x1b = (const bf16_t*)(p.ws + OFF_X1B) + (size_t)tok * DM + d0;
;     const u32x4 xa = *(const u32x4*)x1b, xb = *(const u32x4*)(x1b + 8);
;     const unsigned xw[8] = {xa.x, xa.y, xa.z, xa.w, xb.x, xb.y, xb.z, xb.w};
; #pragma unroll
;     for (int i = 0; i < 4; i++) {
;         const int d = d0 + i * 4;
;         const f32x4 xv = {bf_lo(xw[2 * i]), bf_hi(xw[2 * i]), bf_lo(xw[2 * i + 1]), bf_hi(xw[2 * i + 1])};
;         const f32x4 gt = *(const f32x4*)(mod + b * 6144 + 5 * 1024 + d);
	v_lshlrev_b32_e32 v78, 16, v58
	v_pk_fma_f32 v[28:29], s[4:5], v[6:7], v[52:53] op_sel_hi:[0,1,1]
	v_cvt_scalef32_pk_f32_fp4 v[6:7], v40, 1.0 op_sel:[1,0,0]
	v_pk_fma_f32 v[32:33], s[4:5], v[6:7], v[50:51] op_sel_hi:[0,1,1]
	v_cvt_scalef32_pk_f32_fp4 v[6:7], v40, 1.0 op_sel:[0,1,0]
	v_pk_fma_f32 v[48:49], s[4:5], v[6:7], v[48:49] op_sel_hi:[0,1,1]
	v_cvt_scalef32_pk_f32_fp4 v[6:7], v40, 1.0 op_sel:[1,1,0]
	v_pk_fma_f32 v[46:47], s[4:5], v[6:7], v[46:47] op_sel_hi:[0,1,1]
	v_cvt_scalef32_pk_f32_fp4 v[6:7], v41, 1.0
	v_pk_fma_f32 v[44:45], s[4:5], v[6:7], v[44:45] op_sel_hi:[0,1,1]
	v_cvt_scalef32_pk_f32_fp4 v[6:7], v41, 1.0 op_sel:[1,0,0]
	v_pk_fma_f32 v[42:43], s[4:5], v[6:7], v[42:43] op_sel_hi:[0,1,1]
	v_cvt_scalef32_pk_f32_fp4 v[6:7], v41, 1.0 op_sel:[0,1,0]
	v_pk_fma_f32 v[50:51], s[4:5], v[6:7], v[54:55] op_sel_hi:[0,1,1]
	v_cvt_scalef32_pk_f32_fp4 v[6:7], v41, 1.0 op_sel:[1,1,0]
	v_pk_fma_f32 v[40:41], s[4:5], v[6:7], v[56:57] op_sel_hi:[0,1,1]
	global_load_dwordx4 v[4:7], v[4:5], off offset:48
	v_readlane_b32 s4, v9, 2
	v_cvt_scalef32_pk_f32_fp4 v[52:53], v38, 1.0
	v_and_b32_e32 v79, 0xffff0000, v58
	v_pk_fma_f32 v[28:29], s[4:5], v[52:53], v[28:29] op_sel_hi:[0,1,1]
	v_cvt_scalef32_pk_f32_fp4 v[52:53], v38, 1.0 op_sel:[1,0,0]
	v_pk_fma_f32 v[32:33], s[4:5], v[52:53], v[32:33] op_sel_hi:[0,1,1]
	v_cvt_scalef32_pk_f32_fp4 v[52:53], v38, 1.0 op_sel:[0,1,0]
	v_pk_fma_f32 v[48:49], s[4:5], v[52:53], v[48:49] op_sel_hi:[0,1,1]
	v_cvt_scalef32_pk_f32_fp4 v[52:53], v38, 1.0 op_sel:[1,1,0]
	v_pk_fma_f32 v[46:47], s[4:5], v[52:53], v[46:47] op_sel_hi:[0,1,1]
	v_cvt_scalef32_pk_f32_fp4 v[52:53], v39, 1.0
	v_pk_fma_f32 v[44:45], s[4:5], v[52:53], v[44:45] op_sel_hi:[0,1,1]
	v_cvt_scalef32_pk_f32_fp4 v[52:53], v39, 1.0 op_sel:[1,0,0]
	v_pk_fma_f32 v[42:43], s[4:5], v[52:53], v[42:43] op_sel_hi:[0,1,1]
	v_cvt_scalef32_pk_f32_fp4 v[52:53], v39, 1.0 op_sel:[0,1,0]
	v_cvt_scalef32_pk_f32_fp4 v[38:39], v39, 1.0 op_sel:[1,1,0]
	v_pk_fma_f32 v[50:51], s[4:5], v[52:53], v[50:51] op_sel_hi:[0,1,1]
	v_pk_fma_f32 v[38:39], s[4:5], v[38:39], v[40:41] op_sel_hi:[0,1,1]
	v_readlane_b32 s4, v9, 1
	v_cvt_scalef32_pk_f32_fp4 v[40:41], v36, 1.0
	v_lshlrev_b32_e32 v58, 16, v59
	v_pk_fma_f32 v[28:29], s[4:5], v[40:41], v[28:29] op_sel_hi:[0,1,1]
	v_cvt_scalef32_pk_f32_fp4 v[40:41], v36, 1.0 op_sel:[1,0,0]
	v_pk_fma_f32 v[32:33], s[4:5], v[40:41], v[32:33] op_sel_hi:[0,1,1]
	v_cvt_scalef32_pk_f32_fp4 v[40:41], v36, 1.0 op_sel:[0,1,0]
	v_pk_fma_f32 v[40:41], s[4:5], v[40:41], v[48:49] op_sel_hi:[0,1,1]
	v_cvt_scalef32_pk_f32_fp4 v[48:49], v36, 1.0 op_sel:[1,1,0]
	v_pk_fma_f32 v[46:47], s[4:5], v[48:49], v[46:47] op_sel_hi:[0,1,1]
	v_cvt_scalef32_pk_f32_fp4 v[48:49], v37, 1.0
	v_pk_fma_f32 v[44:45], s[4:5], v[48:49], v[44:45] op_sel_hi:[0,1,1]
	v_cvt_scalef32_pk_f32_fp4 v[48:49], v37, 1.0 op_sel:[1,0,0]
	v_pk_fma_f32 v[42:43], s[4:5], v[48:49], v[42:43] op_sel_hi:[0,1,1]
	v_cvt_scalef32_pk_f32_fp4 v[48:49], v37, 1.0 op_sel:[0,1,0]
	v_cvt_scalef32_pk_f32_fp4 v[36:37], v37, 1.0 op_sel:[1,1,0]
	v_pk_fma_f32 v[48:49], s[4:5], v[48:49], v[50:51] op_sel_hi:[0,1,1]
	v_pk_fma_f32 v[36:37], s[4:5], v[36:37], v[38:39] op_sel_hi:[0,1,1]
	v_readlane_b32 s4, v9, 3
	v_cvt_scalef32_pk_f32_fp4 v[38:39], v34, 1.0
	v_and_b32_e32 v59, 0xffff0000, v59
	v_pk_fma_f32 v[28:29], s[4:5], v[38:39], v[28:29] op_sel_hi:[0,1,1]
	v_cvt_scalef32_pk_f32_fp4 v[38:39], v34, 1.0 op_sel:[1,0,0]
	v_pk_fma_f32 v[50:51], s[4:5], v[38:39], v[32:33] op_sel_hi:[0,1,1]
	v_cvt_scalef32_pk_f32_fp4 v[32:33], v34, 1.0 op_sel:[0,1,0]
	v_pk_fma_f32 v[52:53], s[4:5], v[32:33], v[40:41] op_sel_hi:[0,1,1]
	v_cvt_scalef32_pk_f32_fp4 v[32:33], v34, 1.0 op_sel:[1,1,0]
	v_pk_fma_f32 v[54:55], s[4:5], v[32:33], v[46:47] op_sel_hi:[0,1,1]
	v_cvt_scalef32_pk_f32_fp4 v[32:33], v35, 1.0
	v_pk_fma_f32 v[56:57], s[4:5], v[32:33], v[44:45] op_sel_hi:[0,1,1]
	v_cvt_scalef32_pk_f32_fp4 v[32:33], v35, 1.0 op_sel:[1,0,0]
	v_pk_fma_f32 v[74:75], s[4:5], v[32:33], v[42:43] op_sel_hi:[0,1,1]
	v_cvt_scalef32_pk_f32_fp4 v[32:33], v35, 1.0 op_sel:[0,1,0]
	v_pk_fma_f32 v[48:49], s[4:5], v[32:33], v[48:49] op_sel_hi:[0,1,1]
	v_cvt_scalef32_pk_f32_fp4 v[32:33], v35, 1.0 op_sel:[1,1,0]
	v_pk_fma_f32 v[76:77], s[4:5], v[32:33], v[36:37] op_sel_hi:[0,1,1]
	global_load_dwordx4 v[32:35], v[24:25], off offset:48
	global_load_dwordx4 v[36:39], v[24:25], off offset:32
	global_load_dwordx4 v[40:43], v[24:25], off offset:16
	global_load_dwordx4 v[44:47], v[24:25], off
	s_waitcnt vmcnt(7)
; __device__ __forceinline__ float bf_lo(unsigned u) { return __uint_as_float(u << 16); }
; __device__ __forceinline__ float bf_hi(unsigned u) { return __uint_as_float(u & 0xffff0000u); }
; __device__ __forceinline__ int vblk() { return (int)blockIdx.x * 2 + half_id(); }
; __device__ __forceinline__ int vgrid() { return (int)gridDim.x * 2; }
; __device__ __forceinline__ void p3_finish(const Params& p, float* dstp, int tok, int lane, const f32x2 (&acc)[8], float* tr) {
;     ...
;     const bf16_t* x1b = (const bf16_t*)(p.ws + OFF_X1B) + (size_t)tok * DM + d0;
;     const u32x4 xa = *(const u32x4*)x1b, xb = *(const u32x4*)(x1b + 8);
;     const unsigned xw[8] = {xa.x, xa.y, xa.z, xa.w, xb.x, xb.y, xb.z, xb.w};
; #pragma unroll
;     for (int i = 0; i < 4; i++) {
;         const int d = d0 + i * 4;
;         const f32x4 xv = {bf_lo(xw[2 * i]), bf_hi(xw[2 * i]), bf_lo(xw[2 * i + 1]), bf_hi(xw[2 * i + 1])};
;         const f32x4 gt = *(const f32x4*)(mod + b * 6144 + 5 * 1024 + d);
; #pragma unroll
;         for (int j = 0; j < 4; j++) { const float v = xv[j] + gt[j] * own[i * 4 + j]; x2[i * 4 + j] = v; ss += v * v; }
;     }
;     ss = wave_sum(ss);
;     const float rstd = rsqrtf(ss * (1.f / 1024.f) + 1e-6f);
; #pragma unroll
;     for (int i = 0; i < 4; i++) {
;         const int d = d0 + i * 4;
;         const f32x4 fg = *(const f32x4*)(p.final_g + d);
;         f32x4 o;
; #pragma unroll
;         for (int j = 0; j < 4; j++) o[j] = x2[i * 4 + j] * rstd * fg[j];
;         *(f32x4*)(tr + d) = o;
;     }
;     __builtin_amdgcn_fence(__ATOMIC_RELEASE, "wavefront");
;     __builtin_amdgcn_wave_barrier();
;     __builtin_amdgcn_fence(__ATOMIC_ACQUIRE, "wavefront");
; #pragma unroll
;     for (int j = 0; j < 4; j++) {
;         const f32x4 v = *(const f32x4*)(tr + j * 256 + lane * 4);
;         *(f32x4*)(dstp + (size_t)tok * DM + j * 256 + lane * 4) = v;
;     }
;     __builtin_amdgcn_wave_barrier();
; }
; __device__ void phaseP3(const Params& p, float* dstp, char* lds) {
;     ...
;     for (int tb = (vblk() * 4 + wave) * TPW; tb < NTOK; tb += vgrid() * 4 * TPW) {
	v_pk_fma_f32 v[28:29], v[28:29], v[62:63], v[78:79]
	v_pk_fma_f32 v[50:51], v[50:51], v[64:65], v[58:59]
	v_pk_mul_f32 v[62:63], v[28:29], v[28:29]
	v_pk_mul_f32 v[58:59], v[50:51], v[50:51]
	v_lshlrev_b32_e32 v64, 16, v60
	v_and_b32_e32 v65, 0xffff0000, v60
	v_add_f32_e32 v9, v62, v63
	s_waitcnt vmcnt(5)
	v_pk_fma_f32 v[52:53], v[52:53], v[70:71], v[64:65]
	v_add_f32_e32 v9, v58, v9
	v_pk_mul_f32 v[64:65], v[52:53], v[52:53]
	v_lshlrev_b32_e32 v60, 16, v61
	v_and_b32_e32 v61, 0xffff0000, v61
	v_add_f32_e32 v9, v59, v9
	v_pk_fma_f32 v[54:55], v[54:55], v[72:73], v[60:61]
	v_add_f32_e32 v9, v64, v9
	v_pk_mul_f32 v[60:61], v[54:55], v[54:55]
	v_lshlrev_b32_e32 v70, 16, v0
	v_and_b32_e32 v71, 0xffff0000, v0
	v_add_f32_e32 v9, v65, v9
	v_pk_fma_f32 v[56:57], v[56:57], v[66:67], v[70:71]
	v_add_f32_e32 v9, v60, v9
	v_pk_mul_f32 v[66:67], v[56:57], v[56:57]
	v_lshlrev_b32_e32 v0, 16, v1
	v_and_b32_e32 v1, 0xffff0000, v1
	v_add_f32_e32 v9, v61, v9
	v_pk_fma_f32 v[68:69], v[74:75], v[68:69], v[0:1]
	v_add_f32_e32 v9, v66, v9
	v_pk_mul_f32 v[0:1], v[68:69], v[68:69]
	v_lshlrev_b32_e32 v70, 16, v2
	v_and_b32_e32 v71, 0xffff0000, v2
	v_add_f32_e32 v9, v67, v9
	s_waitcnt vmcnt(4)
	v_pk_fma_f32 v[4:5], v[48:49], v[4:5], v[70:71]
	v_add_f32_e32 v0, v0, v9
	v_pk_mul_f32 v[48:49], v[4:5], v[4:5]
	v_lshlrev_b32_e32 v2, 16, v3
	v_and_b32_e32 v3, 0xffff0000, v3
	v_add_f32_e32 v0, v1, v0
	v_pk_fma_f32 v[6:7], v[76:77], v[6:7], v[2:3]
	v_add_f32_e32 v0, v48, v0
	v_pk_mul_f32 v[2:3], v[6:7], v[6:7]
	v_add_f32_e32 v0, v49, v0
	v_add_f32_e32 v0, v2, v0
	v_add_f32_e32 v0, v3, v0
	ds_bpermute_b32 v1, v112, v0
	s_waitcnt lgkmcnt(0)
	v_add_f32_e32 v0, v0, v1
	ds_bpermute_b32 v1, v113, v0
	s_waitcnt lgkmcnt(0)
	v_add_f32_e32 v0, v0, v1
	ds_bpermute_b32 v1, v114, v0
	s_waitcnt lgkmcnt(0)
	v_add_f32_e32 v0, v0, v1
	ds_bpermute_b32 v1, v115, v0
	s_waitcnt lgkmcnt(0)
	v_add_f32_e32 v0, v0, v1
	ds_bpermute_b32 v1, v116, v0
	s_waitcnt lgkmcnt(0)
	v_add_f32_e32 v0, v0, v1
	ds_bpermute_b32 v1, v117, v0
	s_waitcnt lgkmcnt(0)
	v_add_f32_e32 v0, v0, v1
	v_fmamk_f32 v0, v0, 0x3a800000, v130
	v_mul_f32_e32 v1, 0x4b800000, v0
	v_cmp_gt_f32_e32 vcc, s38, v0
	s_nop 1
	v_cndmask_b32_e32 v0, v0, v1, vcc
	v_rsq_f32_e32 v0, v0
	s_nop 0
	v_mul_f32_e32 v1, 0x45800000, v0
	v_cndmask_b32_e32 v12, v0, v1, vcc
	v_pk_mul_f32 v[0:1], v[28:29], v[12:13] op_sel_hi:[1,0]
	v_pk_mul_f32 v[2:3], v[50:51], v[12:13] op_sel_hi:[1,0]
	s_waitcnt vmcnt(0)
	v_pk_mul_f32 v[0:1], v[44:45], v[0:1]
	v_pk_mul_f32 v[2:3], v[46:47], v[2:3]
	ds_write_b128 v118, v[0:3]
	v_pk_mul_f32 v[0:1], v[52:53], v[12:13] op_sel_hi:[1,0]
	v_pk_mul_f32 v[2:3], v[54:55], v[12:13] op_sel_hi:[1,0]
	v_pk_mul_f32 v[0:1], v[40:41], v[0:1]
	v_pk_mul_f32 v[2:3], v[42:43], v[2:3]
	ds_write_b128 v118, v[0:3] offset:16
	v_pk_mul_f32 v[0:1], v[56:57], v[12:13] op_sel_hi:[1,0]
	v_pk_mul_f32 v[2:3], v[68:69], v[12:13] op_sel_hi:[1,0]
	v_pk_mul_f32 v[0:1], v[36:37], v[0:1]
	v_pk_mul_f32 v[2:3], v[38:39], v[2:3]
	ds_write_b128 v118, v[0:3] offset:32
	v_pk_mul_f32 v[0:1], v[4:5], v[12:13] op_sel_hi:[1,0]
	v_pk_mul_f32 v[2:3], v[6:7], v[12:13] op_sel_hi:[1,0]
	v_pk_mul_f32 v[0:1], v[32:33], v[0:1]
	v_pk_mul_f32 v[2:3], v[34:35], v[2:3]
	ds_write_b128 v118, v[0:3] offset:48
	ds_read_b128 v[0:3], v128
	ds_read_b128 v[4:7], v128 offset:1024
	v_lshlrev_b64 v[32:33], 12, v[30:31]
	v_lshl_add_u64 v[32:33], v[18:19], 0, v[32:33]
	ds_read_b128 v[28:31], v128 offset:2048
	s_waitcnt lgkmcnt(2)
	global_store_dwordx4 v[32:33], v[0:3], off
	s_waitcnt lgkmcnt(1)
	global_store_dwordx4 v[32:33], v[4:7], off offset:1024
	ds_read_b128 v[0:3], v128 offset:3072
	v_cmp_lt_i32_e32 vcc, s41, v8
	s_or_b64 s[28:29], vcc, s[28:29]
	s_waitcnt lgkmcnt(1)
	global_store_dwordx4 v[32:33], v[28:31], off offset:2048
	s_waitcnt lgkmcnt(0)
	global_store_dwordx4 v[32:33], v[0:3], off offset:3072
	s_andn2_b64 exec, exec, s[28:29]
	s_cbranch_execnz .LBB0_1042
